# v61 + residual epilogues: row sum-of-squares reduction across lane halves with v_permlane16_swap / v_permlane32_swap (copy, swap, add) instead of ds_bpermute LDS round trips (41 of 48 sites)
# baseline (speedup 1.0000x reference)
; __device__ __forceinline__ unsigned cvt_pk_bf16(float lo, float hi) { unsigned r; asm volatile("v_cvt_pk_bf16_f32 %0, %1, %2" : "=v"(r) : "v"(lo), "v"(hi)); return r; }
;     __device__ __forceinline__ void operator()(const f32x4 (&acc)[2][2][4][2], const Unit& u, int wr, int wc, int fr, int fq) const {
;     ...
;             for (int m = 0; m < 4; ++m) { const int row = row0 + ai * HALF + m * 16; const size_t off = (size_t)row * 1024 + col0; float s = 0.f;
; #pragma unroll
;                 for (int bj = 0; bj < 2; ++bj) { f32x4 b0, b1;
;                     if (base32) { b0 = *(const f32x4*)(base32 + off + bj * HALF); b1 = *(const f32x4*)(base32 + off + bj * HALF + 4); }
;                     else { const u32x4 hv = hv4[m][bj];
;                         b0 = (f32x4){__builtin_bit_cast(float, hv.x << 16), __builtin_bit_cast(float, hv.x & 0xffff0000u), __builtin_bit_cast(float, hv.y << 16), __builtin_bit_cast(float, hv.y & 0xffff0000u)};
;                         b1 = (f32x4){__builtin_bit_cast(float, hv.z << 16), __builtin_bit_cast(float, hv.z & 0xffff0000u), __builtin_bit_cast(float, hv.w << 16), __builtin_bit_cast(float, hv.w & 0xffff0000u)}; }
;                     const f32x4 o0 = b0 + acc[ai][bj][m][0], o1 = b1 + acc[ai][bj][m][1];
;                     s += ((o0[0] * o0[0] + o0[1] * o0[1]) + (o0[2] * o0[2] + o0[3] * o0[3])) + ((o1[0] * o1[0] + o1[1] * o1[1]) + (o1[2] * o1[2] + o1[3] * o1[3]));
;                     u32x4 w; w.x = cvt_pk_bf16(o0[0], o0[1]); w.y = cvt_pk_bf16(o0[2], o0[3]); w.z = cvt_pk_bf16(o1[0], o1[1]); w.w = cvt_pk_bf16(o1[2], o1[3]); *(u32x4*)(hb + off + bj * HALF) = w; }
;                 s += __shfl_xor(s, 16); s += __shfl_xor(s, 32);
;                 if (fq == 0) P[(wr * 64 + ai * HALF + m * 16 + fr) * 4 + wc] = s;
.LBB0_647:
	s_waitcnt vmcnt(0)
	v_pk_add_f32 v[152:153], v[152:153], v[156:157]
	v_pk_add_f32 v[150:151], v[150:151], v[154:155]
	v_pk_add_f32 v[156:157], v[146:147], v[158:159]
	v_mul_f32_e32 v146, v151, v151
	v_mul_f32_e32 v147, v153, v153
	v_pk_add_f32 v[154:155], v[148:149], v[160:161]
	v_fmac_f32_e32 v146, v150, v150
	v_fmac_f32_e32 v147, v152, v152
	v_add_f32_e32 v146, v146, v147
	v_mul_f32_e32 v147, v157, v157
	v_mul_f32_e32 v148, v155, v155
	v_fmac_f32_e32 v147, v156, v156
	v_fmac_f32_e32 v148, v154, v154
	v_mul_f32_e32 v168, v201, v201
	v_mul_f32_e32 v169, v197, v197
	v_mul_f32_e32 v167, v167, v167
	v_mul_f32_e32 v165, v165, v165
	v_add_f32_e32 v147, v147, v148
	v_and_b32_e32 v148, 64, v225
	v_fmac_f32_e32 v168, v200, v200
	v_fmac_f32_e32 v169, v196, v196
	v_fmac_f32_e32 v167, v166, v166
	v_fmac_f32_e32 v165, v164, v164
	v_add_f32_e32 v146, v147, v146
	v_xor_b32_e32 v147, 16, v225
	v_add_u32_e32 v158, 64, v148
	v_add_f32_e32 v168, v168, v169
	v_add_f32_e32 v164, v167, v165
	v_cmp_lt_i32_e32 vcc, v147, v158
	v_add_f32_e32 v164, v164, v168
	v_add_f32_e32 v146, v164, v146
	v_cndmask_b32_e32 v147, v225, v147, vcc
	v_lshlrev_b32_e32 v164, 2, v147
	v_mov_b32_e32 v147, v146
	s_nop 1
	v_permlane16_swap_b32 v146, v147
	s_nop 1
	v_cmp_eq_u32_e64 s[12:13], 0, v206
	v_cvt_pk_bf16_f32 v148, v150, v151
	v_cvt_pk_bf16_f32 v149, v152, v153
	v_cvt_pk_bf16_f32 v150, v156, v157
	s_waitcnt lgkmcnt(0)
	v_add_f32_e32 v146, v146, v147
	v_xor_b32_e32 v147, 32, v225
	v_cmp_lt_i32_e32 vcc, v147, v158
	v_cvt_pk_bf16_f32 v151, v154, v155
	global_store_dwordx4 v[162:163], v[148:151], off offset:256
	v_lshl_add_u32 v162, v207, 4, s53
	v_cndmask_b32_e32 v147, v225, v147, vcc
	v_lshlrev_b32_e32 v165, 2, v147
	v_mov_b32_e32 v147, v146
	s_nop 1
	v_permlane32_swap_b32 v146, v147
	s_nop 1
	s_and_saveexec_b64 s[36:37], s[12:13]
	s_cbranch_execz .LBB0_649
	s_waitcnt lgkmcnt(0)
	v_add_f32_e32 v146, v146, v147
	ds_write_b32 v162, v146

; __device__ __forceinline__ unsigned cvt_pk_bf16(float lo, float hi) { unsigned r; asm volatile("v_cvt_pk_bf16_f32 %0, %1, %2" : "=v"(r) : "v"(lo), "v"(hi)); return r; }
;     __device__ __forceinline__ void operator()(const f32x4 (&acc)[2][2][4][2], const Unit& u, int wr, int wc, int fr, int fq) const {
;     ...
;             for (int m = 0; m < 4; ++m) { const int row = row0 + ai * HALF + m * 16; const size_t off = (size_t)row * 1024 + col0; float s = 0.f;
; #pragma unroll
;                 for (int bj = 0; bj < 2; ++bj) { f32x4 b0, b1;
;                     if (base32) { b0 = *(const f32x4*)(base32 + off + bj * HALF); b1 = *(const f32x4*)(base32 + off + bj * HALF + 4); }
;                     else { const u32x4 hv = hv4[m][bj];
;                         b0 = (f32x4){__builtin_bit_cast(float, hv.x << 16), __builtin_bit_cast(float, hv.x & 0xffff0000u), __builtin_bit_cast(float, hv.y << 16), __builtin_bit_cast(float, hv.y & 0xffff0000u)};
;                         b1 = (f32x4){__builtin_bit_cast(float, hv.z << 16), __builtin_bit_cast(float, hv.z & 0xffff0000u), __builtin_bit_cast(float, hv.w << 16), __builtin_bit_cast(float, hv.w & 0xffff0000u)}; }
;                     const f32x4 o0 = b0 + acc[ai][bj][m][0], o1 = b1 + acc[ai][bj][m][1];
;                     s += ((o0[0] * o0[0] + o0[1] * o0[1]) + (o0[2] * o0[2] + o0[3] * o0[3])) + ((o1[0] * o1[0] + o1[1] * o1[1]) + (o1[2] * o1[2] + o1[3] * o1[3]));
;                     u32x4 w; w.x = cvt_pk_bf16(o0[0], o0[1]); w.y = cvt_pk_bf16(o0[2], o0[3]); w.z = cvt_pk_bf16(o1[0], o1[1]); w.w = cvt_pk_bf16(o1[2], o1[3]); *(u32x4*)(hb + off + bj * HALF) = w; }
;                 s += __shfl_xor(s, 16); s += __shfl_xor(s, 32);
;                 if (fq == 0) P[(wr * 64 + ai * HALF + m * 16 + fr) * 4 + wc] = s;
.LBB0_655:
	s_waitcnt vmcnt(0)
	v_pk_add_f32 v[128:129], v[128:129], v[140:141]
	v_pk_add_f32 v[126:127], v[126:127], v[138:139]
	v_pk_add_f32 v[140:141], v[122:123], v[142:143]
	v_mul_f32_e32 v122, v127, v127
	v_mul_f32_e32 v123, v129, v129
	v_pk_add_f32 v[138:139], v[124:125], v[144:145]
	v_fmac_f32_e32 v122, v126, v126
	v_fmac_f32_e32 v123, v128, v128
	v_mul_f32_e32 v152, v161, v161
	v_mul_f32_e32 v153, v157, v157
	v_mul_f32_e32 v151, v151, v151
	v_mul_f32_e32 v149, v149, v149
	v_add_f32_e32 v122, v122, v123
	v_mul_f32_e32 v123, v141, v141
	v_mul_f32_e32 v124, v139, v139
	v_fmac_f32_e32 v152, v160, v160
	v_fmac_f32_e32 v153, v156, v156
	v_fmac_f32_e32 v151, v150, v150
	v_fmac_f32_e32 v149, v148, v148
	v_fmac_f32_e32 v123, v140, v140
	v_fmac_f32_e32 v124, v138, v138
	v_add_f32_e32 v152, v152, v153
	v_add_f32_e32 v148, v151, v149
	v_add_f32_e32 v123, v123, v124
	v_add_f32_e32 v148, v148, v152
	v_add_f32_e32 v122, v123, v122
	v_add_f32_e32 v122, v148, v122
	v_mov_b32_e32 v123, v122
	s_nop 1
	v_permlane16_swap_b32 v122, v123
	s_nop 1
	v_cvt_pk_bf16_f32 v124, v126, v127
	v_cvt_pk_bf16_f32 v125, v128, v129
	v_cvt_pk_bf16_f32 v126, v140, v141
	v_cvt_pk_bf16_f32 v127, v138, v139
	s_waitcnt lgkmcnt(0)
	v_add_f32_e32 v122, v122, v123
	v_mov_b32_e32 v123, v122
	s_nop 1
	v_permlane32_swap_b32 v122, v123
	s_nop 1
	global_store_dwordx4 v[146:147], v[124:127], off offset:256
	s_and_saveexec_b64 s[36:37], s[12:13]
	s_cbranch_execz .LBB0_657
	s_waitcnt lgkmcnt(0)
	v_add_f32_e32 v122, v122, v123
	ds_write_b32 v162, v122 offset:256

; __device__ __forceinline__ unsigned cvt_pk_bf16(float lo, float hi) { unsigned r; asm volatile("v_cvt_pk_bf16_f32 %0, %1, %2" : "=v"(r) : "v"(lo), "v"(hi)); return r; }
;     __device__ __forceinline__ void operator()(const f32x4 (&acc)[2][2][4][2], const Unit& u, int wr, int wc, int fr, int fq) const {
;     ...
;             for (int m = 0; m < 4; ++m) { const int row = row0 + ai * HALF + m * 16; const size_t off = (size_t)row * 1024 + col0; float s = 0.f;
; #pragma unroll
;                 for (int bj = 0; bj < 2; ++bj) { f32x4 b0, b1;
;                     if (base32) { b0 = *(const f32x4*)(base32 + off + bj * HALF); b1 = *(const f32x4*)(base32 + off + bj * HALF + 4); }
;                     else { const u32x4 hv = hv4[m][bj];
;                         b0 = (f32x4){__builtin_bit_cast(float, hv.x << 16), __builtin_bit_cast(float, hv.x & 0xffff0000u), __builtin_bit_cast(float, hv.y << 16), __builtin_bit_cast(float, hv.y & 0xffff0000u)};
;                         b1 = (f32x4){__builtin_bit_cast(float, hv.z << 16), __builtin_bit_cast(float, hv.z & 0xffff0000u), __builtin_bit_cast(float, hv.w << 16), __builtin_bit_cast(float, hv.w & 0xffff0000u)}; }
;                     const f32x4 o0 = b0 + acc[ai][bj][m][0], o1 = b1 + acc[ai][bj][m][1];
;                     s += ((o0[0] * o0[0] + o0[1] * o0[1]) + (o0[2] * o0[2] + o0[3] * o0[3])) + ((o1[0] * o1[0] + o1[1] * o1[1]) + (o1[2] * o1[2] + o1[3] * o1[3]));
;                     u32x4 w; w.x = cvt_pk_bf16(o0[0], o0[1]); w.y = cvt_pk_bf16(o0[2], o0[3]); w.z = cvt_pk_bf16(o1[0], o1[1]); w.w = cvt_pk_bf16(o1[2], o1[3]); *(u32x4*)(hb + off + bj * HALF) = w; }
;                 s += __shfl_xor(s, 16); s += __shfl_xor(s, 32);
;                 if (fq == 0) P[(wr * 64 + ai * HALF + m * 16 + fr) * 4 + wc] = s;
.LBB0_663:
	s_waitcnt vmcnt(0)
	v_pk_add_f32 v[104:105], v[104:105], v[112:113]
	v_pk_add_f32 v[102:103], v[102:103], v[110:111]
	v_pk_add_f32 v[112:113], v[98:99], v[114:115]
	v_mul_f32_e32 v98, v103, v103
	v_mul_f32_e32 v99, v105, v105
	v_pk_add_f32 v[110:111], v[100:101], v[116:117]
	v_fmac_f32_e32 v98, v102, v102
	v_fmac_f32_e32 v99, v104, v104
	v_mul_f32_e32 v128, v145, v145
	v_mul_f32_e32 v129, v141, v141
	v_mul_f32_e32 v127, v127, v127
	v_mul_f32_e32 v125, v125, v125
	v_add_f32_e32 v98, v98, v99
	v_mul_f32_e32 v99, v113, v113
	v_mul_f32_e32 v100, v111, v111
	v_fmac_f32_e32 v128, v144, v144
	v_fmac_f32_e32 v129, v140, v140
	v_fmac_f32_e32 v127, v126, v126
	v_fmac_f32_e32 v125, v124, v124
	v_fmac_f32_e32 v99, v112, v112
	v_fmac_f32_e32 v100, v110, v110
	v_add_f32_e32 v128, v128, v129
	v_add_f32_e32 v124, v127, v125
	v_add_f32_e32 v99, v99, v100
	v_add_f32_e32 v124, v124, v128
	v_add_f32_e32 v98, v99, v98
	v_add_f32_e32 v98, v124, v98
	v_mov_b32_e32 v99, v98
	s_nop 1
	v_permlane16_swap_b32 v98, v99
	s_nop 1
	v_cvt_pk_bf16_f32 v100, v102, v103
	v_cvt_pk_bf16_f32 v101, v104, v105
	v_cvt_pk_bf16_f32 v102, v112, v113
	v_cvt_pk_bf16_f32 v103, v110, v111
	s_waitcnt lgkmcnt(0)
	v_add_f32_e32 v98, v98, v99
	v_mov_b32_e32 v99, v98
	s_nop 1
	v_permlane32_swap_b32 v98, v99
	s_nop 1
	global_store_dwordx4 v[122:123], v[100:103], off offset:256
	s_and_saveexec_b64 s[36:37], s[12:13]
	s_cbranch_execz .LBB0_665
	s_waitcnt lgkmcnt(0)
	v_add_f32_e32 v98, v98, v99
	ds_write_b32 v162, v98 offset:512

; __device__ __forceinline__ unsigned cvt_pk_bf16(float lo, float hi) { unsigned r; asm volatile("v_cvt_pk_bf16_f32 %0, %1, %2" : "=v"(r) : "v"(lo), "v"(hi)); return r; }
;     __device__ __forceinline__ void operator()(const f32x4 (&acc)[2][2][4][2], const Unit& u, int wr, int wc, int fr, int fq) const {
;     ...
;             for (int m = 0; m < 4; ++m) { const int row = row0 + ai * HALF + m * 16; const size_t off = (size_t)row * 1024 + col0; float s = 0.f;
; #pragma unroll
;                 for (int bj = 0; bj < 2; ++bj) { f32x4 b0, b1;
;                     if (base32) { b0 = *(const f32x4*)(base32 + off + bj * HALF); b1 = *(const f32x4*)(base32 + off + bj * HALF + 4); }
;                     else { const u32x4 hv = hv4[m][bj];
;                         b0 = (f32x4){__builtin_bit_cast(float, hv.x << 16), __builtin_bit_cast(float, hv.x & 0xffff0000u), __builtin_bit_cast(float, hv.y << 16), __builtin_bit_cast(float, hv.y & 0xffff0000u)};
;                         b1 = (f32x4){__builtin_bit_cast(float, hv.z << 16), __builtin_bit_cast(float, hv.z & 0xffff0000u), __builtin_bit_cast(float, hv.w << 16), __builtin_bit_cast(float, hv.w & 0xffff0000u)}; }
;                     const f32x4 o0 = b0 + acc[ai][bj][m][0], o1 = b1 + acc[ai][bj][m][1];
;                     s += ((o0[0] * o0[0] + o0[1] * o0[1]) + (o0[2] * o0[2] + o0[3] * o0[3])) + ((o1[0] * o1[0] + o1[1] * o1[1]) + (o1[2] * o1[2] + o1[3] * o1[3]));
;                     u32x4 w; w.x = cvt_pk_bf16(o0[0], o0[1]); w.y = cvt_pk_bf16(o0[2], o0[3]); w.z = cvt_pk_bf16(o1[0], o1[1]); w.w = cvt_pk_bf16(o1[2], o1[3]); *(u32x4*)(hb + off + bj * HALF) = w; }
;                 s += __shfl_xor(s, 16); s += __shfl_xor(s, 32);
;                 if (fq == 0) P[(wr * 64 + ai * HALF + m * 16 + fr) * 4 + wc] = s;
.LBB0_671:
	s_waitcnt vmcnt(0)
	v_pk_add_f32 v[80:81], v[80:81], v[88:89]
	v_pk_add_f32 v[78:79], v[78:79], v[86:87]
	v_pk_add_f32 v[88:89], v[74:75], v[90:91]
	v_mul_f32_e32 v74, v79, v79
	v_mul_f32_e32 v75, v81, v81
	v_pk_add_f32 v[86:87], v[76:77], v[92:93]
	v_fmac_f32_e32 v74, v78, v78
	v_fmac_f32_e32 v75, v80, v80
	v_mul_f32_e32 v104, v117, v117
	v_mul_f32_e32 v105, v113, v113
	v_mul_f32_e32 v103, v103, v103
	v_mul_f32_e32 v101, v101, v101
	v_add_f32_e32 v74, v74, v75
	v_mul_f32_e32 v75, v89, v89
	v_mul_f32_e32 v76, v87, v87
	v_fmac_f32_e32 v104, v116, v116
	v_fmac_f32_e32 v105, v112, v112
	v_fmac_f32_e32 v103, v102, v102
	v_fmac_f32_e32 v101, v100, v100
	v_fmac_f32_e32 v75, v88, v88
	v_fmac_f32_e32 v76, v86, v86
	v_add_f32_e32 v104, v104, v105
	v_add_f32_e32 v100, v103, v101
	v_add_f32_e32 v75, v75, v76
	v_add_f32_e32 v100, v100, v104
	v_add_f32_e32 v74, v75, v74
	v_add_f32_e32 v74, v100, v74
	v_mov_b32_e32 v75, v74
	s_nop 1
	v_permlane16_swap_b32 v74, v75
	s_nop 1
	v_cvt_pk_bf16_f32 v76, v78, v79
	v_cvt_pk_bf16_f32 v77, v80, v81
	v_cvt_pk_bf16_f32 v78, v88, v89
	v_cvt_pk_bf16_f32 v79, v86, v87
	s_waitcnt lgkmcnt(0)
	v_add_f32_e32 v74, v74, v75
	v_mov_b32_e32 v75, v74
	s_nop 1
	v_permlane32_swap_b32 v74, v75
	s_nop 1
	global_store_dwordx4 v[98:99], v[76:79], off offset:256
	s_and_saveexec_b64 s[36:37], s[12:13]
	s_cbranch_execz .LBB0_673
	s_waitcnt lgkmcnt(0)
	v_add_f32_e32 v74, v74, v75
	ds_write_b32 v162, v74 offset:768

; __device__ __forceinline__ unsigned cvt_pk_bf16(float lo, float hi) { unsigned r; asm volatile("v_cvt_pk_bf16_f32 %0, %1, %2" : "=v"(r) : "v"(lo), "v"(hi)); return r; }
;     __device__ __forceinline__ void operator()(const f32x4 (&acc)[2][2][4][2], const Unit& u, int wr, int wc, int fr, int fq) const {
;     ...
;             for (int m = 0; m < 4; ++m) { const int row = row0 + ai * HALF + m * 16; const size_t off = (size_t)row * 1024 + col0; float s = 0.f;
; #pragma unroll
;                 for (int bj = 0; bj < 2; ++bj) { f32x4 b0, b1;
;                     if (base32) { b0 = *(const f32x4*)(base32 + off + bj * HALF); b1 = *(const f32x4*)(base32 + off + bj * HALF + 4); }
;                     else { const u32x4 hv = hv4[m][bj];
;                         b0 = (f32x4){__builtin_bit_cast(float, hv.x << 16), __builtin_bit_cast(float, hv.x & 0xffff0000u), __builtin_bit_cast(float, hv.y << 16), __builtin_bit_cast(float, hv.y & 0xffff0000u)};
;                         b1 = (f32x4){__builtin_bit_cast(float, hv.z << 16), __builtin_bit_cast(float, hv.z & 0xffff0000u), __builtin_bit_cast(float, hv.w << 16), __builtin_bit_cast(float, hv.w & 0xffff0000u)}; }
;                     const f32x4 o0 = b0 + acc[ai][bj][m][0], o1 = b1 + acc[ai][bj][m][1];
;                     s += ((o0[0] * o0[0] + o0[1] * o0[1]) + (o0[2] * o0[2] + o0[3] * o0[3])) + ((o1[0] * o1[0] + o1[1] * o1[1]) + (o1[2] * o1[2] + o1[3] * o1[3]));
;                     u32x4 w; w.x = cvt_pk_bf16(o0[0], o0[1]); w.y = cvt_pk_bf16(o0[2], o0[3]); w.z = cvt_pk_bf16(o1[0], o1[1]); w.w = cvt_pk_bf16(o1[2], o1[3]); *(u32x4*)(hb + off + bj * HALF) = w; }
;                 s += __shfl_xor(s, 16); s += __shfl_xor(s, 32);
;                 if (fq == 0) P[(wr * 64 + ai * HALF + m * 16 + fr) * 4 + wc] = s;
.LBB0_682:
	s_waitcnt vmcnt(0)
	v_pk_add_f32 v[56:57], v[56:57], v[60:61]
	v_pk_add_f32 v[54:55], v[54:55], v[58:59]
	v_pk_add_f32 v[60:61], v[50:51], v[62:63]
	v_mul_f32_e32 v50, v55, v55
	v_mul_f32_e32 v51, v57, v57
	v_pk_add_f32 v[58:59], v[52:53], v[64:65]
	v_fmac_f32_e32 v50, v54, v54
	v_fmac_f32_e32 v51, v56, v56
	v_mul_f32_e32 v80, v93, v93
	v_mul_f32_e32 v81, v89, v89
	v_mul_f32_e32 v79, v79, v79
	v_mul_f32_e32 v77, v77, v77
	v_add_f32_e32 v50, v50, v51
	v_mul_f32_e32 v51, v61, v61
	v_mul_f32_e32 v52, v59, v59
	v_fmac_f32_e32 v80, v92, v92
	v_fmac_f32_e32 v81, v88, v88
	v_fmac_f32_e32 v79, v78, v78
	v_fmac_f32_e32 v77, v76, v76
	v_fmac_f32_e32 v51, v60, v60
	v_fmac_f32_e32 v52, v58, v58
	v_add_f32_e32 v80, v80, v81
	v_add_f32_e32 v76, v79, v77
	v_add_f32_e32 v51, v51, v52
	v_add_f32_e32 v76, v76, v80
	v_add_f32_e32 v50, v51, v50
	v_add_f32_e32 v50, v76, v50
	v_mov_b32_e32 v51, v50
	s_nop 1
	v_permlane16_swap_b32 v50, v51
	s_nop 1
	v_cvt_pk_bf16_f32 v52, v54, v55
	v_cvt_pk_bf16_f32 v53, v56, v57
	v_cvt_pk_bf16_f32 v54, v60, v61
	v_cvt_pk_bf16_f32 v55, v58, v59
	s_waitcnt lgkmcnt(0)
	v_add_f32_e32 v50, v50, v51
	v_mov_b32_e32 v51, v50
	s_nop 1
	v_permlane32_swap_b32 v50, v51
	s_nop 1
	global_store_dwordx4 v[74:75], v[52:55], off offset:256
	s_and_saveexec_b64 s[36:37], s[12:13]
	s_cbranch_execz .LBB0_684
	s_waitcnt lgkmcnt(0)
	v_add_f32_e32 v50, v50, v51
	ds_write_b32 v162, v50 offset:2048

; __device__ __forceinline__ unsigned cvt_pk_bf16(float lo, float hi) { unsigned r; asm volatile("v_cvt_pk_bf16_f32 %0, %1, %2" : "=v"(r) : "v"(lo), "v"(hi)); return r; }
;     __device__ __forceinline__ void operator()(const f32x4 (&acc)[2][2][4][2], const Unit& u, int wr, int wc, int fr, int fq) const {
;     ...
;             for (int m = 0; m < 4; ++m) { const int row = row0 + ai * HALF + m * 16; const size_t off = (size_t)row * 1024 + col0; float s = 0.f;
; #pragma unroll
;                 for (int bj = 0; bj < 2; ++bj) { f32x4 b0, b1;
;                     if (base32) { b0 = *(const f32x4*)(base32 + off + bj * HALF); b1 = *(const f32x4*)(base32 + off + bj * HALF + 4); }
;                     else { const u32x4 hv = hv4[m][bj];
;                         b0 = (f32x4){__builtin_bit_cast(float, hv.x << 16), __builtin_bit_cast(float, hv.x & 0xffff0000u), __builtin_bit_cast(float, hv.y << 16), __builtin_bit_cast(float, hv.y & 0xffff0000u)};
;                         b1 = (f32x4){__builtin_bit_cast(float, hv.z << 16), __builtin_bit_cast(float, hv.z & 0xffff0000u), __builtin_bit_cast(float, hv.w << 16), __builtin_bit_cast(float, hv.w & 0xffff0000u)}; }
;                     const f32x4 o0 = b0 + acc[ai][bj][m][0], o1 = b1 + acc[ai][bj][m][1];
;                     s += ((o0[0] * o0[0] + o0[1] * o0[1]) + (o0[2] * o0[2] + o0[3] * o0[3])) + ((o1[0] * o1[0] + o1[1] * o1[1]) + (o1[2] * o1[2] + o1[3] * o1[3]));
;                     u32x4 w; w.x = cvt_pk_bf16(o0[0], o0[1]); w.y = cvt_pk_bf16(o0[2], o0[3]); w.z = cvt_pk_bf16(o1[0], o1[1]); w.w = cvt_pk_bf16(o1[2], o1[3]); *(u32x4*)(hb + off + bj * HALF) = w; }
;                 s += __shfl_xor(s, 16); s += __shfl_xor(s, 32);
;                 if (fq == 0) P[(wr * 64 + ai * HALF + m * 16 + fr) * 4 + wc] = s;
.LBB0_690:
	s_waitcnt vmcnt(0)
	v_pk_add_f32 v[40:41], v[40:41], v[44:45]
	v_pk_add_f32 v[38:39], v[38:39], v[42:43]
	v_pk_add_f32 v[44:45], v[34:35], v[46:47]
	v_mul_f32_e32 v34, v39, v39
	v_mul_f32_e32 v35, v41, v41
	v_pk_add_f32 v[42:43], v[36:37], v[48:49]
	v_fmac_f32_e32 v34, v38, v38
	v_fmac_f32_e32 v35, v40, v40
	v_mul_f32_e32 v56, v65, v65
	v_mul_f32_e32 v57, v61, v61
	v_mul_f32_e32 v55, v55, v55
	v_mul_f32_e32 v53, v53, v53
	v_add_f32_e32 v34, v34, v35
	v_mul_f32_e32 v35, v45, v45
	v_mul_f32_e32 v36, v43, v43
	v_fmac_f32_e32 v56, v64, v64
	v_fmac_f32_e32 v57, v60, v60
	v_fmac_f32_e32 v55, v54, v54
	v_fmac_f32_e32 v53, v52, v52
	v_fmac_f32_e32 v35, v44, v44
	v_fmac_f32_e32 v36, v42, v42
	v_add_f32_e32 v56, v56, v57
	v_add_f32_e32 v52, v55, v53
	v_add_f32_e32 v35, v35, v36
	v_add_f32_e32 v52, v52, v56
	v_add_f32_e32 v34, v35, v34
	v_add_f32_e32 v34, v52, v34
	v_mov_b32_e32 v35, v34
	s_nop 1
	v_permlane16_swap_b32 v34, v35
	s_nop 1
	v_cvt_pk_bf16_f32 v36, v38, v39
	v_cvt_pk_bf16_f32 v37, v40, v41
	v_cvt_pk_bf16_f32 v38, v44, v45
	v_cvt_pk_bf16_f32 v39, v42, v43
	s_waitcnt lgkmcnt(0)
	v_add_f32_e32 v34, v34, v35
	v_mov_b32_e32 v35, v34
	s_nop 1
	v_permlane32_swap_b32 v34, v35
	s_nop 1
	global_store_dwordx4 v[50:51], v[36:39], off offset:256
	s_and_saveexec_b64 s[36:37], s[12:13]
	s_cbranch_execz .LBB0_692
	s_waitcnt lgkmcnt(0)
	v_add_f32_e32 v34, v34, v35
	ds_write_b32 v162, v34 offset:2304

; __device__ __forceinline__ unsigned cvt_pk_bf16(float lo, float hi) { unsigned r; asm volatile("v_cvt_pk_bf16_f32 %0, %1, %2" : "=v"(r) : "v"(lo), "v"(hi)); return r; }
;     __device__ __forceinline__ void operator()(const f32x4 (&acc)[2][2][4][2], const Unit& u, int wr, int wc, int fr, int fq) const {
;     ...
;             for (int m = 0; m < 4; ++m) { const int row = row0 + ai * HALF + m * 16; const size_t off = (size_t)row * 1024 + col0; float s = 0.f;
; #pragma unroll
;                 for (int bj = 0; bj < 2; ++bj) { f32x4 b0, b1;
;                     if (base32) { b0 = *(const f32x4*)(base32 + off + bj * HALF); b1 = *(const f32x4*)(base32 + off + bj * HALF + 4); }
;                     else { const u32x4 hv = hv4[m][bj];
;                         b0 = (f32x4){__builtin_bit_cast(float, hv.x << 16), __builtin_bit_cast(float, hv.x & 0xffff0000u), __builtin_bit_cast(float, hv.y << 16), __builtin_bit_cast(float, hv.y & 0xffff0000u)};
;                         b1 = (f32x4){__builtin_bit_cast(float, hv.z << 16), __builtin_bit_cast(float, hv.z & 0xffff0000u), __builtin_bit_cast(float, hv.w << 16), __builtin_bit_cast(float, hv.w & 0xffff0000u)}; }
;                     const f32x4 o0 = b0 + acc[ai][bj][m][0], o1 = b1 + acc[ai][bj][m][1];
;                     s += ((o0[0] * o0[0] + o0[1] * o0[1]) + (o0[2] * o0[2] + o0[3] * o0[3])) + ((o1[0] * o1[0] + o1[1] * o1[1]) + (o1[2] * o1[2] + o1[3] * o1[3]));
;                     u32x4 w; w.x = cvt_pk_bf16(o0[0], o0[1]); w.y = cvt_pk_bf16(o0[2], o0[3]); w.z = cvt_pk_bf16(o1[0], o1[1]); w.w = cvt_pk_bf16(o1[2], o1[3]); *(u32x4*)(hb + off + bj * HALF) = w; }
;                 s += __shfl_xor(s, 16); s += __shfl_xor(s, 32);
;                 if (fq == 0) P[(wr * 64 + ai * HALF + m * 16 + fr) * 4 + wc] = s;
.LBB0_698:
	s_waitcnt vmcnt(0)
	v_pk_add_f32 v[24:25], v[24:25], v[28:29]
	v_pk_add_f32 v[22:23], v[22:23], v[26:27]
	v_pk_add_f32 v[28:29], v[18:19], v[30:31]
	v_mul_f32_e32 v18, v23, v23
	v_mul_f32_e32 v19, v25, v25
	v_pk_add_f32 v[26:27], v[20:21], v[32:33]
	v_fmac_f32_e32 v18, v22, v22
	v_fmac_f32_e32 v19, v24, v24
	v_mul_f32_e32 v40, v49, v49
	v_mul_f32_e32 v41, v45, v45
	v_mul_f32_e32 v39, v39, v39
	v_mul_f32_e32 v37, v37, v37
	v_add_f32_e32 v18, v18, v19
	v_mul_f32_e32 v19, v29, v29
	v_mul_f32_e32 v20, v27, v27
	v_fmac_f32_e32 v40, v48, v48
	v_fmac_f32_e32 v41, v44, v44
	v_fmac_f32_e32 v39, v38, v38
	v_fmac_f32_e32 v37, v36, v36
	v_fmac_f32_e32 v19, v28, v28
	v_fmac_f32_e32 v20, v26, v26
	v_add_f32_e32 v40, v40, v41
	v_add_f32_e32 v36, v39, v37
	v_add_f32_e32 v19, v19, v20
	v_add_f32_e32 v36, v36, v40
	v_add_f32_e32 v18, v19, v18
	v_add_f32_e32 v18, v36, v18
	v_mov_b32_e32 v19, v18
	s_nop 1
	v_permlane16_swap_b32 v18, v19
	s_nop 1
	v_cvt_pk_bf16_f32 v20, v22, v23
	v_cvt_pk_bf16_f32 v21, v24, v25
	v_cvt_pk_bf16_f32 v22, v28, v29
	v_cvt_pk_bf16_f32 v23, v26, v27
	s_waitcnt lgkmcnt(0)
	v_add_f32_e32 v18, v18, v19
	v_mov_b32_e32 v19, v18
	s_nop 1
	v_permlane32_swap_b32 v18, v19
	s_nop 1
	global_store_dwordx4 v[34:35], v[20:23], off offset:256
	s_and_saveexec_b64 s[36:37], s[12:13]
	s_cbranch_execz .LBB0_700
	s_waitcnt lgkmcnt(0)
	v_add_f32_e32 v18, v18, v19
	ds_write_b32 v162, v18 offset:2560

; __device__ __forceinline__ unsigned cvt_pk_bf16(float lo, float hi) { unsigned r; asm volatile("v_cvt_pk_bf16_f32 %0, %1, %2" : "=v"(r) : "v"(lo), "v"(hi)); return r; }
;     __device__ __forceinline__ void operator()(const f32x4 (&acc)[2][2][4][2], const Unit& u, int wr, int wc, int fr, int fq) const {
;     ...
;             for (int m = 0; m < 4; ++m) { const int row = row0 + ai * HALF + m * 16; const size_t off = (size_t)row * 1024 + col0; float s = 0.f;
; #pragma unroll
;                 for (int bj = 0; bj < 2; ++bj) { f32x4 b0, b1;
;                     if (base32) { b0 = *(const f32x4*)(base32 + off + bj * HALF); b1 = *(const f32x4*)(base32 + off + bj * HALF + 4); }
;                     else { const u32x4 hv = hv4[m][bj];
;                         b0 = (f32x4){__builtin_bit_cast(float, hv.x << 16), __builtin_bit_cast(float, hv.x & 0xffff0000u), __builtin_bit_cast(float, hv.y << 16), __builtin_bit_cast(float, hv.y & 0xffff0000u)};
;                         b1 = (f32x4){__builtin_bit_cast(float, hv.z << 16), __builtin_bit_cast(float, hv.z & 0xffff0000u), __builtin_bit_cast(float, hv.w << 16), __builtin_bit_cast(float, hv.w & 0xffff0000u)}; }
;                     const f32x4 o0 = b0 + acc[ai][bj][m][0], o1 = b1 + acc[ai][bj][m][1];
;                     s += ((o0[0] * o0[0] + o0[1] * o0[1]) + (o0[2] * o0[2] + o0[3] * o0[3])) + ((o1[0] * o1[0] + o1[1] * o1[1]) + (o1[2] * o1[2] + o1[3] * o1[3]));
;                     u32x4 w; w.x = cvt_pk_bf16(o0[0], o0[1]); w.y = cvt_pk_bf16(o0[2], o0[3]); w.z = cvt_pk_bf16(o1[0], o1[1]); w.w = cvt_pk_bf16(o1[2], o1[3]); *(u32x4*)(hb + off + bj * HALF) = w; }
;                 s += __shfl_xor(s, 16); s += __shfl_xor(s, 32);
;                 if (fq == 0) P[(wr * 64 + ai * HALF + m * 16 + fr) * 4 + wc] = s;
.LBB0_706:
	s_waitcnt vmcnt(0)
	v_pk_add_f32 v[8:9], v[8:9], v[12:13]
	v_pk_add_f32 v[6:7], v[6:7], v[10:11]
	v_pk_add_f32 v[12:13], v[2:3], v[14:15]
	v_mul_f32_e32 v2, v7, v7
	v_mul_f32_e32 v3, v9, v9
	v_pk_add_f32 v[10:11], v[4:5], v[16:17]
	v_fmac_f32_e32 v2, v6, v6
	v_fmac_f32_e32 v3, v8, v8
	v_mul_f32_e32 v24, v33, v33
	v_mul_f32_e32 v25, v29, v29
	v_mul_f32_e32 v23, v23, v23
	v_mul_f32_e32 v21, v21, v21
	v_add_f32_e32 v2, v2, v3
	v_mul_f32_e32 v3, v13, v13
	v_mul_f32_e32 v4, v11, v11
	v_fmac_f32_e32 v24, v32, v32
	v_fmac_f32_e32 v25, v28, v28
	v_fmac_f32_e32 v23, v22, v22
	v_fmac_f32_e32 v21, v20, v20
	v_fmac_f32_e32 v3, v12, v12
	v_fmac_f32_e32 v4, v10, v10
	v_add_f32_e32 v24, v24, v25
	v_add_f32_e32 v20, v23, v21
	v_add_f32_e32 v3, v3, v4
	v_add_f32_e32 v20, v20, v24
	v_add_f32_e32 v2, v3, v2
	v_add_f32_e32 v2, v20, v2
	v_mov_b32_e32 v3, v2
	s_nop 1
	v_permlane16_swap_b32 v2, v3
	s_nop 1
	v_cvt_pk_bf16_f32 v4, v6, v7
	v_cvt_pk_bf16_f32 v5, v8, v9
	v_cvt_pk_bf16_f32 v6, v12, v13
	v_cvt_pk_bf16_f32 v7, v10, v11
	s_waitcnt lgkmcnt(0)
	v_add_f32_e32 v2, v2, v3
	v_mov_b32_e32 v3, v2
	s_nop 1
	v_permlane32_swap_b32 v2, v3
	s_nop 1
	global_store_dwordx4 v[18:19], v[4:7], off offset:256
	s_and_saveexec_b64 s[10:11], s[12:13]
	s_cbranch_execz .LBB0_708
	s_waitcnt lgkmcnt(0)
	v_add_f32_e32 v2, v2, v3
	ds_write_b32 v162, v2 offset:2816

; __device__ __forceinline__ unsigned cvt_pk_bf16(float lo, float hi) { unsigned r; asm volatile("v_cvt_pk_bf16_f32 %0, %1, %2" : "=v"(r) : "v"(lo), "v"(hi)); return r; }
;     __device__ __forceinline__ void operator()(const f32x4 (&acc)[2][2][4][2], const Unit& u, int wr, int wc, int fr, int fq) const {
;     ...
;             for (int m = 0; m < 4; ++m) { const int row = row0 + ai * HALF + m * 16; const size_t off = (size_t)row * 1024 + col0; float s = 0.f;
; #pragma unroll
;                 for (int bj = 0; bj < 2; ++bj) { f32x4 b0, b1;
;                     if (base32) { b0 = *(const f32x4*)(base32 + off + bj * HALF); b1 = *(const f32x4*)(base32 + off + bj * HALF + 4); }
;                     else { const u32x4 hv = hv4[m][bj];
;                         b0 = (f32x4){__builtin_bit_cast(float, hv.x << 16), __builtin_bit_cast(float, hv.x & 0xffff0000u), __builtin_bit_cast(float, hv.y << 16), __builtin_bit_cast(float, hv.y & 0xffff0000u)};
;                         b1 = (f32x4){__builtin_bit_cast(float, hv.z << 16), __builtin_bit_cast(float, hv.z & 0xffff0000u), __builtin_bit_cast(float, hv.w << 16), __builtin_bit_cast(float, hv.w & 0xffff0000u)}; }
;                     const f32x4 o0 = b0 + acc[ai][bj][m][0], o1 = b1 + acc[ai][bj][m][1];
;                     s += ((o0[0] * o0[0] + o0[1] * o0[1]) + (o0[2] * o0[2] + o0[3] * o0[3])) + ((o1[0] * o1[0] + o1[1] * o1[1]) + (o1[2] * o1[2] + o1[3] * o1[3]));
;                     u32x4 w; w.x = cvt_pk_bf16(o0[0], o0[1]); w.y = cvt_pk_bf16(o0[2], o0[3]); w.z = cvt_pk_bf16(o1[0], o1[1]); w.w = cvt_pk_bf16(o1[2], o1[3]); *(u32x4*)(hb + off + bj * HALF) = w; }
;                 s += __shfl_xor(s, 16); s += __shfl_xor(s, 32);
;                 if (fq == 0) P[(wr * 64 + ai * HALF + m * 16 + fr) * 4 + wc] = s;
.LBB0_1089:
	s_waitcnt vmcnt(0)
	v_pk_add_f32 v[152:153], v[152:153], v[156:157]
	v_pk_add_f32 v[150:151], v[150:151], v[154:155]
	v_pk_add_f32 v[156:157], v[146:147], v[158:159]
	v_mul_f32_e32 v146, v151, v151
	v_mul_f32_e32 v147, v153, v153
	v_pk_add_f32 v[154:155], v[148:149], v[160:161]
	v_fmac_f32_e32 v146, v150, v150
	v_fmac_f32_e32 v147, v152, v152
	v_add_f32_e32 v146, v146, v147
	v_mul_f32_e32 v147, v157, v157
	v_mul_f32_e32 v148, v155, v155
	v_fmac_f32_e32 v147, v156, v156
	v_fmac_f32_e32 v148, v154, v154
	v_mul_f32_e32 v168, v201, v201
	v_mul_f32_e32 v169, v197, v197
	v_mul_f32_e32 v167, v167, v167
	v_mul_f32_e32 v165, v165, v165
	v_add_f32_e32 v147, v147, v148
	v_and_b32_e32 v148, 64, v225
	v_fmac_f32_e32 v168, v200, v200
	v_fmac_f32_e32 v169, v196, v196
	v_fmac_f32_e32 v167, v166, v166
	v_fmac_f32_e32 v165, v164, v164
	v_add_f32_e32 v146, v147, v146
	v_xor_b32_e32 v147, 16, v225
	v_add_u32_e32 v158, 64, v148
	v_add_f32_e32 v168, v168, v169
	v_add_f32_e32 v164, v167, v165
	v_cmp_lt_i32_e32 vcc, v147, v158
	v_add_f32_e32 v164, v164, v168
	v_add_f32_e32 v146, v164, v146
	v_cndmask_b32_e32 v147, v225, v147, vcc
	v_lshlrev_b32_e32 v164, 2, v147
	v_mov_b32_e32 v147, v146
	s_nop 1
	v_permlane16_swap_b32 v146, v147
	s_nop 1
	v_cmp_eq_u32_e64 s[10:11], 0, v206
	v_cvt_pk_bf16_f32 v148, v150, v151
	v_cvt_pk_bf16_f32 v149, v152, v153
	v_cvt_pk_bf16_f32 v150, v156, v157
	s_waitcnt lgkmcnt(0)
	v_add_f32_e32 v146, v146, v147
	v_xor_b32_e32 v147, 32, v225
	v_cmp_lt_i32_e32 vcc, v147, v158
	v_cvt_pk_bf16_f32 v151, v154, v155
	global_store_dwordx4 v[162:163], v[148:151], off offset:256
	v_lshl_add_u32 v162, v207, 4, s53
	v_cndmask_b32_e32 v147, v225, v147, vcc
	v_lshlrev_b32_e32 v165, 2, v147
	v_mov_b32_e32 v147, v146
	s_nop 1
	v_permlane32_swap_b32 v146, v147
	s_nop 1
	s_and_saveexec_b64 s[36:37], s[10:11]
	s_cbranch_execz .LBB0_1091
	s_waitcnt lgkmcnt(0)
	v_add_f32_e32 v146, v146, v147
	ds_write_b32 v162, v146

; __device__ __forceinline__ unsigned cvt_pk_bf16(float lo, float hi) { unsigned r; asm volatile("v_cvt_pk_bf16_f32 %0, %1, %2" : "=v"(r) : "v"(lo), "v"(hi)); return r; }
;     __device__ __forceinline__ void operator()(const f32x4 (&acc)[2][2][4][2], const Unit& u, int wr, int wc, int fr, int fq) const {
;     ...
;             for (int m = 0; m < 4; ++m) { const int row = row0 + ai * HALF + m * 16; const size_t off = (size_t)row * 1024 + col0; float s = 0.f;
; #pragma unroll
;                 for (int bj = 0; bj < 2; ++bj) { f32x4 b0, b1;
;                     if (base32) { b0 = *(const f32x4*)(base32 + off + bj * HALF); b1 = *(const f32x4*)(base32 + off + bj * HALF + 4); }
;                     else { const u32x4 hv = hv4[m][bj];
;                         b0 = (f32x4){__builtin_bit_cast(float, hv.x << 16), __builtin_bit_cast(float, hv.x & 0xffff0000u), __builtin_bit_cast(float, hv.y << 16), __builtin_bit_cast(float, hv.y & 0xffff0000u)};
;                         b1 = (f32x4){__builtin_bit_cast(float, hv.z << 16), __builtin_bit_cast(float, hv.z & 0xffff0000u), __builtin_bit_cast(float, hv.w << 16), __builtin_bit_cast(float, hv.w & 0xffff0000u)}; }
;                     const f32x4 o0 = b0 + acc[ai][bj][m][0], o1 = b1 + acc[ai][bj][m][1];
;                     s += ((o0[0] * o0[0] + o0[1] * o0[1]) + (o0[2] * o0[2] + o0[3] * o0[3])) + ((o1[0] * o1[0] + o1[1] * o1[1]) + (o1[2] * o1[2] + o1[3] * o1[3]));
;                     u32x4 w; w.x = cvt_pk_bf16(o0[0], o0[1]); w.y = cvt_pk_bf16(o0[2], o0[3]); w.z = cvt_pk_bf16(o1[0], o1[1]); w.w = cvt_pk_bf16(o1[2], o1[3]); *(u32x4*)(hb + off + bj * HALF) = w; }
;                 s += __shfl_xor(s, 16); s += __shfl_xor(s, 32);
;                 if (fq == 0) P[(wr * 64 + ai * HALF + m * 16 + fr) * 4 + wc] = s;
.LBB0_1097:
	s_waitcnt vmcnt(0)
	v_pk_add_f32 v[128:129], v[128:129], v[140:141]
	v_pk_add_f32 v[126:127], v[126:127], v[138:139]
	v_pk_add_f32 v[140:141], v[122:123], v[142:143]
	v_mul_f32_e32 v122, v127, v127
	v_mul_f32_e32 v123, v129, v129
	v_pk_add_f32 v[138:139], v[124:125], v[144:145]
	v_fmac_f32_e32 v122, v126, v126
	v_fmac_f32_e32 v123, v128, v128
	v_mul_f32_e32 v152, v161, v161
	v_mul_f32_e32 v153, v157, v157
	v_mul_f32_e32 v151, v151, v151
	v_mul_f32_e32 v149, v149, v149
	v_add_f32_e32 v122, v122, v123
	v_mul_f32_e32 v123, v141, v141
	v_mul_f32_e32 v124, v139, v139
	v_fmac_f32_e32 v152, v160, v160
	v_fmac_f32_e32 v153, v156, v156
	v_fmac_f32_e32 v151, v150, v150
	v_fmac_f32_e32 v149, v148, v148
	v_fmac_f32_e32 v123, v140, v140
	v_fmac_f32_e32 v124, v138, v138
	v_add_f32_e32 v152, v152, v153
	v_add_f32_e32 v148, v151, v149
	v_add_f32_e32 v123, v123, v124
	v_add_f32_e32 v148, v148, v152
	v_add_f32_e32 v122, v123, v122
	v_add_f32_e32 v122, v148, v122
	v_mov_b32_e32 v123, v122
	s_nop 1
	v_permlane16_swap_b32 v122, v123
	s_nop 1
	v_cvt_pk_bf16_f32 v124, v126, v127
	v_cvt_pk_bf16_f32 v125, v128, v129
	v_cvt_pk_bf16_f32 v126, v140, v141
	v_cvt_pk_bf16_f32 v127, v138, v139
	s_waitcnt lgkmcnt(0)
	v_add_f32_e32 v122, v122, v123
	v_mov_b32_e32 v123, v122
	s_nop 1
	v_permlane32_swap_b32 v122, v123
	s_nop 1
	global_store_dwordx4 v[146:147], v[124:127], off offset:256
	s_and_saveexec_b64 s[36:37], s[10:11]
	s_cbranch_execz .LBB0_1099
	s_waitcnt lgkmcnt(0)
	v_add_f32_e32 v122, v122, v123
	ds_write_b32 v162, v122 offset:256

; __device__ __forceinline__ unsigned cvt_pk_bf16(float lo, float hi) { unsigned r; asm volatile("v_cvt_pk_bf16_f32 %0, %1, %2" : "=v"(r) : "v"(lo), "v"(hi)); return r; }
;     __device__ __forceinline__ void operator()(const f32x4 (&acc)[2][2][4][2], const Unit& u, int wr, int wc, int fr, int fq) const {
;     ...
;             for (int m = 0; m < 4; ++m) { const int row = row0 + ai * HALF + m * 16; const size_t off = (size_t)row * 1024 + col0; float s = 0.f;
; #pragma unroll
;                 for (int bj = 0; bj < 2; ++bj) { f32x4 b0, b1;
;                     if (base32) { b0 = *(const f32x4*)(base32 + off + bj * HALF); b1 = *(const f32x4*)(base32 + off + bj * HALF + 4); }
;                     else { const u32x4 hv = hv4[m][bj];
;                         b0 = (f32x4){__builtin_bit_cast(float, hv.x << 16), __builtin_bit_cast(float, hv.x & 0xffff0000u), __builtin_bit_cast(float, hv.y << 16), __builtin_bit_cast(float, hv.y & 0xffff0000u)};
;                         b1 = (f32x4){__builtin_bit_cast(float, hv.z << 16), __builtin_bit_cast(float, hv.z & 0xffff0000u), __builtin_bit_cast(float, hv.w << 16), __builtin_bit_cast(float, hv.w & 0xffff0000u)}; }
;                     const f32x4 o0 = b0 + acc[ai][bj][m][0], o1 = b1 + acc[ai][bj][m][1];
;                     s += ((o0[0] * o0[0] + o0[1] * o0[1]) + (o0[2] * o0[2] + o0[3] * o0[3])) + ((o1[0] * o1[0] + o1[1] * o1[1]) + (o1[2] * o1[2] + o1[3] * o1[3]));
;                     u32x4 w; w.x = cvt_pk_bf16(o0[0], o0[1]); w.y = cvt_pk_bf16(o0[2], o0[3]); w.z = cvt_pk_bf16(o1[0], o1[1]); w.w = cvt_pk_bf16(o1[2], o1[3]); *(u32x4*)(hb + off + bj * HALF) = w; }
;                 s += __shfl_xor(s, 16); s += __shfl_xor(s, 32);
;                 if (fq == 0) P[(wr * 64 + ai * HALF + m * 16 + fr) * 4 + wc] = s;
.LBB0_1105:
	s_waitcnt vmcnt(0)
	v_pk_add_f32 v[104:105], v[104:105], v[112:113]
	v_pk_add_f32 v[102:103], v[102:103], v[110:111]
	v_pk_add_f32 v[112:113], v[98:99], v[114:115]
	v_mul_f32_e32 v98, v103, v103
	v_mul_f32_e32 v99, v105, v105
	v_pk_add_f32 v[110:111], v[100:101], v[116:117]
	v_fmac_f32_e32 v98, v102, v102
	v_fmac_f32_e32 v99, v104, v104
	v_mul_f32_e32 v128, v145, v145
	v_mul_f32_e32 v129, v141, v141
	v_mul_f32_e32 v127, v127, v127
	v_mul_f32_e32 v125, v125, v125
	v_add_f32_e32 v98, v98, v99
	v_mul_f32_e32 v99, v113, v113
	v_mul_f32_e32 v100, v111, v111
	v_fmac_f32_e32 v128, v144, v144
	v_fmac_f32_e32 v129, v140, v140
	v_fmac_f32_e32 v127, v126, v126
	v_fmac_f32_e32 v125, v124, v124
	v_fmac_f32_e32 v99, v112, v112
	v_fmac_f32_e32 v100, v110, v110
	v_add_f32_e32 v128, v128, v129
	v_add_f32_e32 v124, v127, v125
	v_add_f32_e32 v99, v99, v100
	v_add_f32_e32 v124, v124, v128
	v_add_f32_e32 v98, v99, v98
	v_add_f32_e32 v98, v124, v98
	v_mov_b32_e32 v99, v98
	s_nop 1
	v_permlane16_swap_b32 v98, v99
	s_nop 1
	v_cvt_pk_bf16_f32 v100, v102, v103
	v_cvt_pk_bf16_f32 v101, v104, v105
	v_cvt_pk_bf16_f32 v102, v112, v113
	v_cvt_pk_bf16_f32 v103, v110, v111
	s_waitcnt lgkmcnt(0)
	v_add_f32_e32 v98, v98, v99
	v_mov_b32_e32 v99, v98
	s_nop 1
	v_permlane32_swap_b32 v98, v99
	s_nop 1
	global_store_dwordx4 v[122:123], v[100:103], off offset:256
	s_and_saveexec_b64 s[36:37], s[10:11]
	s_cbranch_execz .LBB0_1107
	s_waitcnt lgkmcnt(0)
	v_add_f32_e32 v98, v98, v99
	ds_write_b32 v162, v98 offset:512

; __device__ __forceinline__ unsigned cvt_pk_bf16(float lo, float hi) { unsigned r; asm volatile("v_cvt_pk_bf16_f32 %0, %1, %2" : "=v"(r) : "v"(lo), "v"(hi)); return r; }
;     __device__ __forceinline__ void operator()(const f32x4 (&acc)[2][2][4][2], const Unit& u, int wr, int wc, int fr, int fq) const {
;     ...
;             for (int m = 0; m < 4; ++m) { const int row = row0 + ai * HALF + m * 16; const size_t off = (size_t)row * 1024 + col0; float s = 0.f;
; #pragma unroll
;                 for (int bj = 0; bj < 2; ++bj) { f32x4 b0, b1;
;                     if (base32) { b0 = *(const f32x4*)(base32 + off + bj * HALF); b1 = *(const f32x4*)(base32 + off + bj * HALF + 4); }
;                     else { const u32x4 hv = hv4[m][bj];
;                         b0 = (f32x4){__builtin_bit_cast(float, hv.x << 16), __builtin_bit_cast(float, hv.x & 0xffff0000u), __builtin_bit_cast(float, hv.y << 16), __builtin_bit_cast(float, hv.y & 0xffff0000u)};
;                         b1 = (f32x4){__builtin_bit_cast(float, hv.z << 16), __builtin_bit_cast(float, hv.z & 0xffff0000u), __builtin_bit_cast(float, hv.w << 16), __builtin_bit_cast(float, hv.w & 0xffff0000u)}; }
;                     const f32x4 o0 = b0 + acc[ai][bj][m][0], o1 = b1 + acc[ai][bj][m][1];
;                     s += ((o0[0] * o0[0] + o0[1] * o0[1]) + (o0[2] * o0[2] + o0[3] * o0[3])) + ((o1[0] * o1[0] + o1[1] * o1[1]) + (o1[2] * o1[2] + o1[3] * o1[3]));
;                     u32x4 w; w.x = cvt_pk_bf16(o0[0], o0[1]); w.y = cvt_pk_bf16(o0[2], o0[3]); w.z = cvt_pk_bf16(o1[0], o1[1]); w.w = cvt_pk_bf16(o1[2], o1[3]); *(u32x4*)(hb + off + bj * HALF) = w; }
;                 s += __shfl_xor(s, 16); s += __shfl_xor(s, 32);
;                 if (fq == 0) P[(wr * 64 + ai * HALF + m * 16 + fr) * 4 + wc] = s;
.LBB0_1113:
	s_waitcnt vmcnt(0)
	v_pk_add_f32 v[80:81], v[80:81], v[88:89]
	v_pk_add_f32 v[78:79], v[78:79], v[86:87]
	v_pk_add_f32 v[88:89], v[74:75], v[90:91]
	v_mul_f32_e32 v74, v79, v79
	v_mul_f32_e32 v75, v81, v81
	v_pk_add_f32 v[86:87], v[76:77], v[92:93]
	v_fmac_f32_e32 v74, v78, v78
	v_fmac_f32_e32 v75, v80, v80
	v_mul_f32_e32 v104, v117, v117
	v_mul_f32_e32 v105, v113, v113
	v_mul_f32_e32 v103, v103, v103
	v_mul_f32_e32 v101, v101, v101
	v_add_f32_e32 v74, v74, v75
	v_mul_f32_e32 v75, v89, v89
	v_mul_f32_e32 v76, v87, v87
	v_fmac_f32_e32 v104, v116, v116
	v_fmac_f32_e32 v105, v112, v112
	v_fmac_f32_e32 v103, v102, v102
	v_fmac_f32_e32 v101, v100, v100
	v_fmac_f32_e32 v75, v88, v88
	v_fmac_f32_e32 v76, v86, v86
	v_add_f32_e32 v104, v104, v105
	v_add_f32_e32 v100, v103, v101
	v_add_f32_e32 v75, v75, v76
	v_add_f32_e32 v100, v100, v104
	v_add_f32_e32 v74, v75, v74
	v_add_f32_e32 v74, v100, v74
	v_mov_b32_e32 v75, v74
	s_nop 1
	v_permlane16_swap_b32 v74, v75
	s_nop 1
	v_cvt_pk_bf16_f32 v76, v78, v79
	v_cvt_pk_bf16_f32 v77, v80, v81
	v_cvt_pk_bf16_f32 v78, v88, v89
	v_cvt_pk_bf16_f32 v79, v86, v87
	s_waitcnt lgkmcnt(0)
	v_add_f32_e32 v74, v74, v75
	v_mov_b32_e32 v75, v74
	s_nop 1
	v_permlane32_swap_b32 v74, v75
	s_nop 1
	global_store_dwordx4 v[98:99], v[76:79], off offset:256
	s_and_saveexec_b64 s[36:37], s[10:11]
	s_cbranch_execz .LBB0_1115
	s_waitcnt lgkmcnt(0)
	v_add_f32_e32 v74, v74, v75
	ds_write_b32 v162, v74 offset:768

; __device__ __forceinline__ unsigned cvt_pk_bf16(float lo, float hi) { unsigned r; asm volatile("v_cvt_pk_bf16_f32 %0, %1, %2" : "=v"(r) : "v"(lo), "v"(hi)); return r; }
;     __device__ __forceinline__ void operator()(const f32x4 (&acc)[2][2][4][2], const Unit& u, int wr, int wc, int fr, int fq) const {
;     ...
;             for (int m = 0; m < 4; ++m) { const int row = row0 + ai * HALF + m * 16; const size_t off = (size_t)row * 1024 + col0; float s = 0.f;
; #pragma unroll
;                 for (int bj = 0; bj < 2; ++bj) { f32x4 b0, b1;
;                     if (base32) { b0 = *(const f32x4*)(base32 + off + bj * HALF); b1 = *(const f32x4*)(base32 + off + bj * HALF + 4); }
;                     else { const u32x4 hv = hv4[m][bj];
;                         b0 = (f32x4){__builtin_bit_cast(float, hv.x << 16), __builtin_bit_cast(float, hv.x & 0xffff0000u), __builtin_bit_cast(float, hv.y << 16), __builtin_bit_cast(float, hv.y & 0xffff0000u)};
;                         b1 = (f32x4){__builtin_bit_cast(float, hv.z << 16), __builtin_bit_cast(float, hv.z & 0xffff0000u), __builtin_bit_cast(float, hv.w << 16), __builtin_bit_cast(float, hv.w & 0xffff0000u)}; }
;                     const f32x4 o0 = b0 + acc[ai][bj][m][0], o1 = b1 + acc[ai][bj][m][1];
;                     s += ((o0[0] * o0[0] + o0[1] * o0[1]) + (o0[2] * o0[2] + o0[3] * o0[3])) + ((o1[0] * o1[0] + o1[1] * o1[1]) + (o1[2] * o1[2] + o1[3] * o1[3]));
;                     u32x4 w; w.x = cvt_pk_bf16(o0[0], o0[1]); w.y = cvt_pk_bf16(o0[2], o0[3]); w.z = cvt_pk_bf16(o1[0], o1[1]); w.w = cvt_pk_bf16(o1[2], o1[3]); *(u32x4*)(hb + off + bj * HALF) = w; }
;                 s += __shfl_xor(s, 16); s += __shfl_xor(s, 32);
;                 if (fq == 0) P[(wr * 64 + ai * HALF + m * 16 + fr) * 4 + wc] = s;
.LBB0_1124:
	s_waitcnt vmcnt(0)
	v_pk_add_f32 v[56:57], v[56:57], v[60:61]
	v_pk_add_f32 v[54:55], v[54:55], v[58:59]
	v_pk_add_f32 v[60:61], v[50:51], v[62:63]
	v_mul_f32_e32 v50, v55, v55
	v_mul_f32_e32 v51, v57, v57
	v_pk_add_f32 v[58:59], v[52:53], v[64:65]
	v_fmac_f32_e32 v50, v54, v54
	v_fmac_f32_e32 v51, v56, v56
	v_mul_f32_e32 v80, v93, v93
	v_mul_f32_e32 v81, v89, v89
	v_mul_f32_e32 v79, v79, v79
	v_mul_f32_e32 v77, v77, v77
	v_add_f32_e32 v50, v50, v51
	v_mul_f32_e32 v51, v61, v61
	v_mul_f32_e32 v52, v59, v59
	v_fmac_f32_e32 v80, v92, v92
	v_fmac_f32_e32 v81, v88, v88
	v_fmac_f32_e32 v79, v78, v78
	v_fmac_f32_e32 v77, v76, v76
	v_fmac_f32_e32 v51, v60, v60
	v_fmac_f32_e32 v52, v58, v58
	v_add_f32_e32 v80, v80, v81
	v_add_f32_e32 v76, v79, v77
	v_add_f32_e32 v51, v51, v52
	v_add_f32_e32 v76, v76, v80
	v_add_f32_e32 v50, v51, v50
	v_add_f32_e32 v50, v76, v50
	v_mov_b32_e32 v51, v50
	s_nop 1
	v_permlane16_swap_b32 v50, v51
	s_nop 1
	v_cvt_pk_bf16_f32 v52, v54, v55
	v_cvt_pk_bf16_f32 v53, v56, v57
	v_cvt_pk_bf16_f32 v54, v60, v61
	v_cvt_pk_bf16_f32 v55, v58, v59
	s_waitcnt lgkmcnt(0)
	v_add_f32_e32 v50, v50, v51
	v_mov_b32_e32 v51, v50
	s_nop 1
	v_permlane32_swap_b32 v50, v51
	s_nop 1
	global_store_dwordx4 v[74:75], v[52:55], off offset:256
	s_and_saveexec_b64 s[36:37], s[10:11]
	s_cbranch_execz .LBB0_1126
	s_waitcnt lgkmcnt(0)
	v_add_f32_e32 v50, v50, v51
	ds_write_b32 v162, v50 offset:2048

; __device__ __forceinline__ unsigned cvt_pk_bf16(float lo, float hi) { unsigned r; asm volatile("v_cvt_pk_bf16_f32 %0, %1, %2" : "=v"(r) : "v"(lo), "v"(hi)); return r; }
;     __device__ __forceinline__ void operator()(const f32x4 (&acc)[2][2][4][2], const Unit& u, int wr, int wc, int fr, int fq) const {
;     ...
;             for (int m = 0; m < 4; ++m) { const int row = row0 + ai * HALF + m * 16; const size_t off = (size_t)row * 1024 + col0; float s = 0.f;
; #pragma unroll
;                 for (int bj = 0; bj < 2; ++bj) { f32x4 b0, b1;
;                     if (base32) { b0 = *(const f32x4*)(base32 + off + bj * HALF); b1 = *(const f32x4*)(base32 + off + bj * HALF + 4); }
;                     else { const u32x4 hv = hv4[m][bj];
;                         b0 = (f32x4){__builtin_bit_cast(float, hv.x << 16), __builtin_bit_cast(float, hv.x & 0xffff0000u), __builtin_bit_cast(float, hv.y << 16), __builtin_bit_cast(float, hv.y & 0xffff0000u)};
;                         b1 = (f32x4){__builtin_bit_cast(float, hv.z << 16), __builtin_bit_cast(float, hv.z & 0xffff0000u), __builtin_bit_cast(float, hv.w << 16), __builtin_bit_cast(float, hv.w & 0xffff0000u)}; }
;                     const f32x4 o0 = b0 + acc[ai][bj][m][0], o1 = b1 + acc[ai][bj][m][1];
;                     s += ((o0[0] * o0[0] + o0[1] * o0[1]) + (o0[2] * o0[2] + o0[3] * o0[3])) + ((o1[0] * o1[0] + o1[1] * o1[1]) + (o1[2] * o1[2] + o1[3] * o1[3]));
;                     u32x4 w; w.x = cvt_pk_bf16(o0[0], o0[1]); w.y = cvt_pk_bf16(o0[2], o0[3]); w.z = cvt_pk_bf16(o1[0], o1[1]); w.w = cvt_pk_bf16(o1[2], o1[3]); *(u32x4*)(hb + off + bj * HALF) = w; }
;                 s += __shfl_xor(s, 16); s += __shfl_xor(s, 32);
;                 if (fq == 0) P[(wr * 64 + ai * HALF + m * 16 + fr) * 4 + wc] = s;
.LBB0_1132:
	s_waitcnt vmcnt(0)
	v_pk_add_f32 v[40:41], v[40:41], v[44:45]
	v_pk_add_f32 v[38:39], v[38:39], v[42:43]
	v_pk_add_f32 v[44:45], v[34:35], v[46:47]
	v_mul_f32_e32 v34, v39, v39
	v_mul_f32_e32 v35, v41, v41
	v_pk_add_f32 v[42:43], v[36:37], v[48:49]
	v_fmac_f32_e32 v34, v38, v38
	v_fmac_f32_e32 v35, v40, v40
	v_mul_f32_e32 v56, v65, v65
	v_mul_f32_e32 v57, v61, v61
	v_mul_f32_e32 v55, v55, v55
	v_mul_f32_e32 v53, v53, v53
	v_add_f32_e32 v34, v34, v35
	v_mul_f32_e32 v35, v45, v45
	v_mul_f32_e32 v36, v43, v43
	v_fmac_f32_e32 v56, v64, v64
	v_fmac_f32_e32 v57, v60, v60
	v_fmac_f32_e32 v55, v54, v54
	v_fmac_f32_e32 v53, v52, v52
	v_fmac_f32_e32 v35, v44, v44
	v_fmac_f32_e32 v36, v42, v42
	v_add_f32_e32 v56, v56, v57
	v_add_f32_e32 v52, v55, v53
	v_add_f32_e32 v35, v35, v36
	v_add_f32_e32 v52, v52, v56
	v_add_f32_e32 v34, v35, v34
	v_add_f32_e32 v34, v52, v34
	v_mov_b32_e32 v35, v34
	s_nop 1
	v_permlane16_swap_b32 v34, v35
	s_nop 1
	v_cvt_pk_bf16_f32 v36, v38, v39
	v_cvt_pk_bf16_f32 v37, v40, v41
	v_cvt_pk_bf16_f32 v38, v44, v45
	v_cvt_pk_bf16_f32 v39, v42, v43
	s_waitcnt lgkmcnt(0)
	v_add_f32_e32 v34, v34, v35
	v_mov_b32_e32 v35, v34
	s_nop 1
	v_permlane32_swap_b32 v34, v35
	s_nop 1
	global_store_dwordx4 v[50:51], v[36:39], off offset:256
	s_and_saveexec_b64 s[36:37], s[10:11]
	s_cbranch_execz .LBB0_1134
	s_waitcnt lgkmcnt(0)
	v_add_f32_e32 v34, v34, v35
	ds_write_b32 v162, v34 offset:2304

; __device__ __forceinline__ unsigned cvt_pk_bf16(float lo, float hi) { unsigned r; asm volatile("v_cvt_pk_bf16_f32 %0, %1, %2" : "=v"(r) : "v"(lo), "v"(hi)); return r; }
;     __device__ __forceinline__ void operator()(const f32x4 (&acc)[2][2][4][2], const Unit& u, int wr, int wc, int fr, int fq) const {
;     ...
;             for (int m = 0; m < 4; ++m) { const int row = row0 + ai * HALF + m * 16; const size_t off = (size_t)row * 1024 + col0; float s = 0.f;
; #pragma unroll
;                 for (int bj = 0; bj < 2; ++bj) { f32x4 b0, b1;
;                     if (base32) { b0 = *(const f32x4*)(base32 + off + bj * HALF); b1 = *(const f32x4*)(base32 + off + bj * HALF + 4); }
;                     else { const u32x4 hv = hv4[m][bj];
;                         b0 = (f32x4){__builtin_bit_cast(float, hv.x << 16), __builtin_bit_cast(float, hv.x & 0xffff0000u), __builtin_bit_cast(float, hv.y << 16), __builtin_bit_cast(float, hv.y & 0xffff0000u)};
;                         b1 = (f32x4){__builtin_bit_cast(float, hv.z << 16), __builtin_bit_cast(float, hv.z & 0xffff0000u), __builtin_bit_cast(float, hv.w << 16), __builtin_bit_cast(float, hv.w & 0xffff0000u)}; }
;                     const f32x4 o0 = b0 + acc[ai][bj][m][0], o1 = b1 + acc[ai][bj][m][1];
;                     s += ((o0[0] * o0[0] + o0[1] * o0[1]) + (o0[2] * o0[2] + o0[3] * o0[3])) + ((o1[0] * o1[0] + o1[1] * o1[1]) + (o1[2] * o1[2] + o1[3] * o1[3]));
;                     u32x4 w; w.x = cvt_pk_bf16(o0[0], o0[1]); w.y = cvt_pk_bf16(o0[2], o0[3]); w.z = cvt_pk_bf16(o1[0], o1[1]); w.w = cvt_pk_bf16(o1[2], o1[3]); *(u32x4*)(hb + off + bj * HALF) = w; }
;                 s += __shfl_xor(s, 16); s += __shfl_xor(s, 32);
;                 if (fq == 0) P[(wr * 64 + ai * HALF + m * 16 + fr) * 4 + wc] = s;
.LBB0_1140:
	s_waitcnt vmcnt(0)
	v_pk_add_f32 v[24:25], v[24:25], v[28:29]
	v_pk_add_f32 v[22:23], v[22:23], v[26:27]
	v_pk_add_f32 v[28:29], v[18:19], v[30:31]
	v_mul_f32_e32 v18, v23, v23
	v_mul_f32_e32 v19, v25, v25
	v_pk_add_f32 v[26:27], v[20:21], v[32:33]
	v_fmac_f32_e32 v18, v22, v22
	v_fmac_f32_e32 v19, v24, v24
	v_mul_f32_e32 v40, v49, v49
	v_mul_f32_e32 v41, v45, v45
	v_mul_f32_e32 v39, v39, v39
	v_mul_f32_e32 v37, v37, v37
	v_add_f32_e32 v18, v18, v19
	v_mul_f32_e32 v19, v29, v29
	v_mul_f32_e32 v20, v27, v27
	v_fmac_f32_e32 v40, v48, v48
	v_fmac_f32_e32 v41, v44, v44
	v_fmac_f32_e32 v39, v38, v38
	v_fmac_f32_e32 v37, v36, v36
	v_fmac_f32_e32 v19, v28, v28
	v_fmac_f32_e32 v20, v26, v26
	v_add_f32_e32 v40, v40, v41
	v_add_f32_e32 v36, v39, v37
	v_add_f32_e32 v19, v19, v20
	v_add_f32_e32 v36, v36, v40
	v_add_f32_e32 v18, v19, v18
	v_add_f32_e32 v18, v36, v18
	v_mov_b32_e32 v19, v18
	s_nop 1
	v_permlane16_swap_b32 v18, v19
	s_nop 1
	v_cvt_pk_bf16_f32 v20, v22, v23
	v_cvt_pk_bf16_f32 v21, v24, v25
	v_cvt_pk_bf16_f32 v22, v28, v29
	v_cvt_pk_bf16_f32 v23, v26, v27
	s_waitcnt lgkmcnt(0)
	v_add_f32_e32 v18, v18, v19
	v_mov_b32_e32 v19, v18
	s_nop 1
	v_permlane32_swap_b32 v18, v19
	s_nop 1
	global_store_dwordx4 v[34:35], v[20:23], off offset:256
	s_and_saveexec_b64 s[36:37], s[10:11]
	s_cbranch_execz .LBB0_1142
	s_waitcnt lgkmcnt(0)
	v_add_f32_e32 v18, v18, v19
	ds_write_b32 v162, v18 offset:2560

; __device__ __forceinline__ unsigned cvt_pk_bf16(float lo, float hi) { unsigned r; asm volatile("v_cvt_pk_bf16_f32 %0, %1, %2" : "=v"(r) : "v"(lo), "v"(hi)); return r; }
;     __device__ __forceinline__ void operator()(const f32x4 (&acc)[2][2][4][2], const Unit& u, int wr, int wc, int fr, int fq) const {
;     ...
;             for (int m = 0; m < 4; ++m) { const int row = row0 + ai * HALF + m * 16; const size_t off = (size_t)row * 1024 + col0; float s = 0.f;
; #pragma unroll
;                 for (int bj = 0; bj < 2; ++bj) { f32x4 b0, b1;
;                     if (base32) { b0 = *(const f32x4*)(base32 + off + bj * HALF); b1 = *(const f32x4*)(base32 + off + bj * HALF + 4); }
;                     else { const u32x4 hv = hv4[m][bj];
;                         b0 = (f32x4){__builtin_bit_cast(float, hv.x << 16), __builtin_bit_cast(float, hv.x & 0xffff0000u), __builtin_bit_cast(float, hv.y << 16), __builtin_bit_cast(float, hv.y & 0xffff0000u)};
;                         b1 = (f32x4){__builtin_bit_cast(float, hv.z << 16), __builtin_bit_cast(float, hv.z & 0xffff0000u), __builtin_bit_cast(float, hv.w << 16), __builtin_bit_cast(float, hv.w & 0xffff0000u)}; }
;                     const f32x4 o0 = b0 + acc[ai][bj][m][0], o1 = b1 + acc[ai][bj][m][1];
;                     s += ((o0[0] * o0[0] + o0[1] * o0[1]) + (o0[2] * o0[2] + o0[3] * o0[3])) + ((o1[0] * o1[0] + o1[1] * o1[1]) + (o1[2] * o1[2] + o1[3] * o1[3]));
;                     u32x4 w; w.x = cvt_pk_bf16(o0[0], o0[1]); w.y = cvt_pk_bf16(o0[2], o0[3]); w.z = cvt_pk_bf16(o1[0], o1[1]); w.w = cvt_pk_bf16(o1[2], o1[3]); *(u32x4*)(hb + off + bj * HALF) = w; }
;                 s += __shfl_xor(s, 16); s += __shfl_xor(s, 32);
;                 if (fq == 0) P[(wr * 64 + ai * HALF + m * 16 + fr) * 4 + wc] = s;
.LBB0_1148:
	s_waitcnt vmcnt(0)
	v_pk_add_f32 v[8:9], v[8:9], v[12:13]
	v_pk_add_f32 v[6:7], v[6:7], v[10:11]
	v_pk_add_f32 v[12:13], v[2:3], v[14:15]
	v_mul_f32_e32 v2, v7, v7
	v_mul_f32_e32 v3, v9, v9
	v_pk_add_f32 v[10:11], v[4:5], v[16:17]
	v_fmac_f32_e32 v2, v6, v6
	v_fmac_f32_e32 v3, v8, v8
	v_mul_f32_e32 v24, v33, v33
	v_mul_f32_e32 v25, v29, v29
	v_mul_f32_e32 v23, v23, v23
	v_mul_f32_e32 v21, v21, v21
	v_add_f32_e32 v2, v2, v3
	v_mul_f32_e32 v3, v13, v13
	v_mul_f32_e32 v4, v11, v11
	v_fmac_f32_e32 v24, v32, v32
	v_fmac_f32_e32 v25, v28, v28
	v_fmac_f32_e32 v23, v22, v22
	v_fmac_f32_e32 v21, v20, v20
	v_fmac_f32_e32 v3, v12, v12
	v_fmac_f32_e32 v4, v10, v10
	v_add_f32_e32 v24, v24, v25
	v_add_f32_e32 v20, v23, v21
	v_add_f32_e32 v3, v3, v4
	v_add_f32_e32 v20, v20, v24
	v_add_f32_e32 v2, v3, v2
	v_add_f32_e32 v2, v20, v2
	v_mov_b32_e32 v3, v2
	s_nop 1
	v_permlane16_swap_b32 v2, v3
	s_nop 1
	v_cvt_pk_bf16_f32 v4, v6, v7
	v_cvt_pk_bf16_f32 v5, v8, v9
	v_cvt_pk_bf16_f32 v6, v12, v13
	v_cvt_pk_bf16_f32 v7, v10, v11
	s_waitcnt lgkmcnt(0)
	v_add_f32_e32 v2, v2, v3
	v_mov_b32_e32 v3, v2
	s_nop 1
	v_permlane32_swap_b32 v2, v3
	s_nop 1
	global_store_dwordx4 v[18:19], v[4:7], off offset:256
	s_and_saveexec_b64 s[8:9], s[10:11]
	s_cbranch_execz .LBB0_1150
	s_waitcnt lgkmcnt(0)
	v_add_f32_e32 v2, v2, v3
	ds_write_b32 v162, v2 offset:2816

; __device__ __forceinline__ unsigned cvt_pk_bf16(float lo, float hi) { unsigned r; asm volatile("v_cvt_pk_bf16_f32 %0, %1, %2" : "=v"(r) : "v"(lo), "v"(hi)); return r; }
;     __device__ __forceinline__ void operator()(const f32x4 (&acc)[2][2][4][2], const Unit& u, int wr, int wc, int fr, int fq) const {
;     ...
;         const int row0 = row_off + u.pm * BM + wr * 64 + fr, col0 = u.pn * BM + wc * 32 + 8 * fq;
; #pragma unroll
;         for (int ai = 0; ai < 2; ++ai) {
;             u32x4 hv4[4][2];
;             if (!base32) {
; #pragma unroll
;                 for (int m = 0; m < 4; ++m)
; #pragma unroll
;                     for (int bj = 0; bj < 2; ++bj) hv4[m][bj] = *(const u32x4*)(hb + (size_t)(row0 + ai * HALF + m * 16) * 1024 + col0 + bj * HALF);
;             }
; #pragma unroll
;             for (int m = 0; m < 4; ++m) { const int row = row0 + ai * HALF + m * 16; const size_t off = (size_t)row * 1024 + col0; float s = 0.f;
; #pragma unroll
;                 for (int bj = 0; bj < 2; ++bj) { f32x4 b0, b1;
;                     if (base32) { b0 = *(const f32x4*)(base32 + off + bj * HALF); b1 = *(const f32x4*)(base32 + off + bj * HALF + 4); }
;                     else { const u32x4 hv = hv4[m][bj];
;                         b0 = (f32x4){__builtin_bit_cast(float, hv.x << 16), __builtin_bit_cast(float, hv.x & 0xffff0000u), __builtin_bit_cast(float, hv.y << 16), __builtin_bit_cast(float, hv.y & 0xffff0000u)};
;                         b1 = (f32x4){__builtin_bit_cast(float, hv.z << 16), __builtin_bit_cast(float, hv.z & 0xffff0000u), __builtin_bit_cast(float, hv.w << 16), __builtin_bit_cast(float, hv.w & 0xffff0000u)}; }
;                     const f32x4 o0 = b0 + acc[ai][bj][m][0], o1 = b1 + acc[ai][bj][m][1];
;                     s += ((o0[0] * o0[0] + o0[1] * o0[1]) + (o0[2] * o0[2] + o0[3] * o0[3])) + ((o1[0] * o1[0] + o1[1] * o1[1]) + (o1[2] * o1[2] + o1[3] * o1[3]));
;                     u32x4 w; w.x = cvt_pk_bf16(o0[0], o0[1]); w.y = cvt_pk_bf16(o0[2], o0[3]); w.z = cvt_pk_bf16(o1[0], o1[1]); w.w = cvt_pk_bf16(o1[2], o1[3]); *(u32x4*)(hb + off + bj * HALF) = w; }
;                 s += __shfl_xor(s, 16); s += __shfl_xor(s, 32);
;                 if (fq == 0) P[(wr * 64 + ai * HALF + m * 16 + fr) * 4 + wc] = s;
.LBB0_1363:
	s_lshl_b32 s8, s16, 8
	v_mov_b32_e32 v187, v184
	v_mov_b32_e32 v188, v1
	s_or_b32 s8, s8, s40
	s_lshl_b32 s17, s17, 8
	v_add_u32_e32 v189, s39, v187
	v_lshl_add_u32 v166, v188, 3, s8
	v_add_u32_e32 v170, s17, v189
	v_ashrrev_i32_e32 v167, 31, v166
	v_lshlrev_b64 v[198:199], 1, v[166:167]
	v_ashrrev_i32_e32 v171, 31, v170
	v_lshl_add_u64 v[168:169], s[10:11], 0, v[198:199]
	v_lshlrev_b64 v[200:201], 11, v[170:171]
	v_lshl_add_u64 v[114:115], v[168:169], 0, v[200:201]
	global_load_dwordx4 v[190:193], v[114:115], off
	global_load_dwordx4 v[194:197], v[114:115], off offset:256
	v_lshl_add_u64 v[182:183], v[200:201], 0, s[66:67]
	s_mov_b64 s[8:9], 0x10000
	v_lshl_add_u64 v[114:115], v[168:169], 0, v[182:183]
	v_lshl_add_u64 v[180:181], v[200:201], 0, s[8:9]
	s_mov_b64 s[8:9], 0x18000
	global_load_dwordx4 v[150:153], v[114:115], off
	global_load_dwordx4 v[146:149], v[114:115], off offset:256
	v_lshl_add_u64 v[114:115], v[168:169], 0, v[180:181]
	v_lshl_add_u64 v[172:173], v[200:201], 0, s[8:9]
	global_load_dwordx4 v[134:137], v[114:115], off
	global_load_dwordx4 v[122:125], v[114:115], off offset:256
	v_lshl_add_u64 v[114:115], v[168:169], 0, v[172:173]
	global_load_dwordx4 v[118:121], v[114:115], off
	s_nop 0
	global_load_dwordx4 v[114:117], v[114:115], off offset:256
	v_cmp_eq_u32_e32 vcc, 0, v188
	s_waitcnt vmcnt(0)
	v_lshlrev_b32_e32 v202, 16, v190
	v_and_b32_e32 v203, 0xffff0000, v190
	v_lshlrev_b32_e32 v190, 16, v191
	v_and_b32_e32 v191, 0xffff0000, v191
	v_lshlrev_b32_e32 v204, 16, v192
	v_and_b32_e32 v205, 0xffff0000, v192
	v_lshlrev_b32_e32 v192, 16, v193
	v_and_b32_e32 v193, 0xffff0000, v193
	v_pk_add_f32 v[144:145], v[144:145], v[190:191]
	v_pk_add_f32 v[142:143], v[142:143], v[202:203]
	v_pk_add_f32 v[190:191], v[140:141], v[192:193]
	v_pk_add_f32 v[140:141], v[138:139], v[204:205]
	v_mul_f32_e32 v138, v143, v143
	v_mul_f32_e32 v139, v145, v145
	v_fmac_f32_e32 v138, v142, v142
	v_fmac_f32_e32 v139, v144, v144
	v_add_f32_e32 v138, v138, v139
	v_mul_f32_e32 v139, v141, v141
	v_mul_f32_e32 v192, v191, v191
	v_fmac_f32_e32 v139, v140, v140
	v_fmac_f32_e32 v192, v190, v190
	v_add_f32_e32 v139, v139, v192
	v_add_f32_e32 v192, v138, v139
	v_cvt_pk_bf16_f32 v138, v142, v143
	v_lshl_add_u64 v[142:143], s[10:11], 0, v[200:201]
	v_cvt_pk_bf16_f32 v139, v144, v145
	v_cvt_pk_bf16_f32 v140, v140, v141
	v_cvt_pk_bf16_f32 v141, v190, v191
	v_lshl_add_u64 v[142:143], v[142:143], 0, v[198:199]
	global_store_dwordx4 v[142:143], v[138:141], off
	v_lshlrev_b32_e32 v144, 16, v196
	v_and_b32_e32 v145, 0xffff0000, v196
	v_lshlrev_b32_e32 v138, 16, v194
	v_and_b32_e32 v139, 0xffff0000, v194
	v_lshlrev_b32_e32 v140, 16, v195
	v_and_b32_e32 v141, 0xffff0000, v195
	v_lshlrev_b32_e32 v190, 16, v197
	v_and_b32_e32 v191, 0xffff0000, v197
	v_pk_add_f32 v[132:133], v[132:133], v[140:141]
	v_pk_add_f32 v[130:131], v[130:131], v[138:139]
	v_pk_add_f32 v[138:139], v[128:129], v[190:191]
	v_pk_add_f32 v[128:129], v[126:127], v[144:145]
	v_mul_f32_e32 v126, v131, v131
	v_mul_f32_e32 v127, v133, v133
	v_fmac_f32_e32 v126, v130, v130
	v_fmac_f32_e32 v127, v132, v132
	v_add_f32_e32 v126, v126, v127
	v_mul_f32_e32 v127, v129, v129
	v_mul_f32_e32 v140, v139, v139
	v_fmac_f32_e32 v127, v128, v128
	v_fmac_f32_e32 v140, v138, v138
	v_add_f32_e32 v127, v127, v140
	v_add_f32_e32 v126, v126, v127
	v_add_f32_e32 v140, v192, v126
	v_cvt_pk_bf16_f32 v126, v130, v131
	v_cvt_pk_bf16_f32 v127, v132, v133
	v_cvt_pk_bf16_f32 v128, v128, v129
	v_cvt_pk_bf16_f32 v129, v138, v139
	global_store_dwordx4 v[142:143], v[126:129], off offset:256
	s_nop 1
	v_and_b32_e32 v127, 64, v225
	v_xor_b32_e32 v126, 16, v225
	v_add_u32_e32 v127, 64, v127
	v_cmp_lt_i32_e64 s[8:9], v126, v127
	s_nop 1
	v_cndmask_b32_e64 v126, v225, v126, s[8:9]
	v_lshlrev_b32_e32 v126, 2, v126
	v_mov_b32_e32 v128, v140
	v_mov_b32_e32 v129, v140
	s_nop 1
	v_permlane16_swap_b32 v129, v128
	s_nop 1
	s_waitcnt lgkmcnt(0)
	v_add_f32_e32 v129, v129, v128
	v_xor_b32_e32 v128, 32, v225
	v_cmp_lt_i32_e64 s[8:9], v128, v127
	s_nop 1
	v_cndmask_b32_e64 v127, v225, v128, s[8:9]
	v_lshlrev_b32_e32 v127, 2, v127
	v_mov_b32_e32 v130, v129
	s_nop 1
	v_permlane32_swap_b32 v129, v130
	s_nop 1
	v_lshl_add_u32 v128, v189, 4, s44
	s_and_saveexec_b64 s[8:9], vcc
	s_cbranch_execz .LBB0_1365
	s_waitcnt lgkmcnt(0)
	v_add_f32_e32 v129, v129, v130
	ds_write_b32 v128, v129
.LBB0_1365:
	s_or_b64 exec, exec, s[8:9]
	s_waitcnt lgkmcnt(0)
	v_lshlrev_b32_e32 v130, 16, v150
	v_and_b32_e32 v131, 0xffff0000, v150
	v_lshlrev_b32_e32 v132, 16, v151
	v_and_b32_e32 v133, 0xffff0000, v151
	v_lshlrev_b32_e32 v138, 16, v152
	v_and_b32_e32 v139, 0xffff0000, v152
	v_lshlrev_b32_e32 v140, 16, v153
	v_and_b32_e32 v141, 0xffff0000, v153
	v_pk_add_f32 v[112:113], v[112:113], v[132:133]
	v_pk_add_f32 v[110:111], v[110:111], v[130:131]
	v_pk_add_f32 v[130:131], v[108:109], v[140:141]
	v_pk_add_f32 v[108:109], v[106:107], v[138:139]
	v_mul_f32_e32 v106, v111, v111
	v_mul_f32_e32 v107, v113, v113
	v_fmac_f32_e32 v106, v110, v110
	v_fmac_f32_e32 v107, v112, v112
	v_add_f32_e32 v106, v106, v107
	v_mul_f32_e32 v107, v109, v109
	v_mul_f32_e32 v129, v131, v131
	v_fmac_f32_e32 v107, v108, v108
	v_fmac_f32_e32 v129, v130, v130
	v_add_f32_e32 v107, v107, v129
	v_add_f32_e32 v129, v106, v107
	v_cvt_pk_bf16_f32 v106, v110, v111
	v_cvt_pk_bf16_f32 v107, v112, v113
	v_lshlrev_b32_e32 v110, 16, v146
	v_and_b32_e32 v111, 0xffff0000, v146
	v_lshlrev_b32_e32 v112, 16, v147
	v_and_b32_e32 v113, 0xffff0000, v147
	v_cvt_pk_bf16_f32 v108, v108, v109
	v_cvt_pk_bf16_f32 v109, v130, v131
	v_lshlrev_b32_e32 v130, 16, v148
	v_and_b32_e32 v131, 0xffff0000, v148
	v_pk_add_f32 v[104:105], v[104:105], v[112:113]
	v_pk_add_f32 v[102:103], v[102:103], v[110:111]
	v_lshlrev_b32_e32 v132, 16, v149
	v_and_b32_e32 v133, 0xffff0000, v149
	v_pk_add_f32 v[112:113], v[98:99], v[130:131]
	v_mul_f32_e32 v98, v103, v103
	v_mul_f32_e32 v99, v105, v105
	v_pk_add_f32 v[110:111], v[100:101], v[132:133]
	v_fmac_f32_e32 v98, v102, v102
	v_fmac_f32_e32 v99, v104, v104
	v_add_f32_e32 v98, v98, v99
	v_mul_f32_e32 v99, v113, v113
	v_mul_f32_e32 v100, v111, v111
	v_fmac_f32_e32 v99, v112, v112
	v_fmac_f32_e32 v100, v110, v110
	v_add_f32_e32 v99, v99, v100
	v_add_f32_e32 v98, v98, v99
	v_add_f32_e32 v101, v129, v98
	ds_bpermute_b32 v129, v126, v101
	v_lshl_add_u64 v[98:99], s[10:11], 0, v[182:183]
	v_lshl_add_u64 v[130:131], v[166:167], 1, v[98:99]
	global_store_dwordx4 v[130:131], v[106:109], off
	v_cvt_pk_bf16_f32 v100, v102, v103
	s_waitcnt lgkmcnt(0)
	v_add_f32_e32 v98, v101, v129
	v_mov_b32_e32 v99, v98
	s_nop 1
	v_permlane32_swap_b32 v98, v99
	s_nop 1
	v_cvt_pk_bf16_f32 v101, v104, v105
	v_cvt_pk_bf16_f32 v102, v112, v113
	v_cvt_pk_bf16_f32 v103, v110, v111
	global_store_dwordx4 v[130:131], v[100:103], off offset:256
	s_and_saveexec_b64 s[8:9], vcc
	s_cbranch_execz .LBB0_1367
	s_waitcnt lgkmcnt(0)
	v_add_f32_e32 v98, v98, v99
	ds_write_b32 v128, v98 offset:256
; __device__ __forceinline__ unsigned cvt_pk_bf16(float lo, float hi) { unsigned r; asm volatile("v_cvt_pk_bf16_f32 %0, %1, %2" : "=v"(r) : "v"(lo), "v"(hi)); return r; }
;     __device__ __forceinline__ void operator()(const f32x4 (&acc)[2][2][4][2], const Unit& u, int wr, int wc, int fr, int fq) const {
;     ...
;             for (int m = 0; m < 4; ++m) { const int row = row0 + ai * HALF + m * 16; const size_t off = (size_t)row * 1024 + col0; float s = 0.f;
; #pragma unroll
;                 for (int bj = 0; bj < 2; ++bj) { f32x4 b0, b1;
;                     if (base32) { b0 = *(const f32x4*)(base32 + off + bj * HALF); b1 = *(const f32x4*)(base32 + off + bj * HALF + 4); }
;                     else { const u32x4 hv = hv4[m][bj];
;                         b0 = (f32x4){__builtin_bit_cast(float, hv.x << 16), __builtin_bit_cast(float, hv.x & 0xffff0000u), __builtin_bit_cast(float, hv.y << 16), __builtin_bit_cast(float, hv.y & 0xffff0000u)};
;                         b1 = (f32x4){__builtin_bit_cast(float, hv.z << 16), __builtin_bit_cast(float, hv.z & 0xffff0000u), __builtin_bit_cast(float, hv.w << 16), __builtin_bit_cast(float, hv.w & 0xffff0000u)}; }
;                     const f32x4 o0 = b0 + acc[ai][bj][m][0], o1 = b1 + acc[ai][bj][m][1];
;                     s += ((o0[0] * o0[0] + o0[1] * o0[1]) + (o0[2] * o0[2] + o0[3] * o0[3])) + ((o1[0] * o1[0] + o1[1] * o1[1]) + (o1[2] * o1[2] + o1[3] * o1[3]));
;                     u32x4 w; w.x = cvt_pk_bf16(o0[0], o0[1]); w.y = cvt_pk_bf16(o0[2], o0[3]); w.z = cvt_pk_bf16(o1[0], o1[1]); w.w = cvt_pk_bf16(o1[2], o1[3]); *(u32x4*)(hb + off + bj * HALF) = w; }
;                 s += __shfl_xor(s, 16); s += __shfl_xor(s, 32);
;                 if (fq == 0) P[(wr * 64 + ai * HALF + m * 16 + fr) * 4 + wc] = s;
.LBB0_1367:
	s_or_b64 exec, exec, s[8:9]
	v_lshlrev_b32_e32 v98, 16, v134
	s_waitcnt lgkmcnt(0)
	v_and_b32_e32 v99, 0xffff0000, v134
	v_lshlrev_b32_e32 v100, 16, v135
	v_and_b32_e32 v101, 0xffff0000, v135
	v_lshlrev_b32_e32 v102, 16, v136
	v_and_b32_e32 v103, 0xffff0000, v136
	v_lshlrev_b32_e32 v104, 16, v137
	v_and_b32_e32 v105, 0xffff0000, v137
	v_pk_add_f32 v[96:97], v[96:97], v[100:101]
	v_pk_add_f32 v[94:95], v[94:95], v[98:99]
	v_pk_add_f32 v[98:99], v[92:93], v[104:105]
	v_pk_add_f32 v[92:93], v[90:91], v[102:103]
	v_mul_f32_e32 v90, v95, v95
	v_mul_f32_e32 v91, v97, v97
	v_fmac_f32_e32 v90, v94, v94
	v_fmac_f32_e32 v91, v96, v96
	v_add_f32_e32 v90, v90, v91
	v_mul_f32_e32 v91, v93, v93
	v_mul_f32_e32 v100, v99, v99
	v_fmac_f32_e32 v91, v92, v92
	v_fmac_f32_e32 v100, v98, v98
	v_add_f32_e32 v91, v91, v100
	v_add_f32_e32 v102, v90, v91
	v_cvt_pk_bf16_f32 v90, v94, v95
	v_cvt_pk_bf16_f32 v91, v96, v97
	v_lshlrev_b32_e32 v94, 16, v122
	v_and_b32_e32 v95, 0xffff0000, v122
	v_lshlrev_b32_e32 v96, 16, v123
	v_and_b32_e32 v97, 0xffff0000, v123
	v_cvt_pk_bf16_f32 v92, v92, v93
	v_cvt_pk_bf16_f32 v93, v98, v99
	v_lshlrev_b32_e32 v98, 16, v124
	v_and_b32_e32 v99, 0xffff0000, v124
	v_pk_add_f32 v[88:89], v[88:89], v[96:97]
	v_pk_add_f32 v[86:87], v[86:87], v[94:95]
	v_lshlrev_b32_e32 v100, 16, v125
	v_and_b32_e32 v101, 0xffff0000, v125
	v_pk_add_f32 v[96:97], v[82:83], v[98:99]
	v_mul_f32_e32 v82, v87, v87
	v_mul_f32_e32 v83, v89, v89
	v_pk_add_f32 v[94:95], v[84:85], v[100:101]
	v_fmac_f32_e32 v82, v86, v86
	v_fmac_f32_e32 v83, v88, v88
	v_add_f32_e32 v82, v82, v83
	v_mul_f32_e32 v83, v97, v97
	v_mul_f32_e32 v84, v95, v95
	v_fmac_f32_e32 v83, v96, v96
	v_fmac_f32_e32 v84, v94, v94
	v_add_f32_e32 v83, v83, v84
	v_add_f32_e32 v82, v82, v83
	v_add_f32_e32 v85, v102, v82
	ds_bpermute_b32 v100, v126, v85
	v_lshl_add_u64 v[82:83], s[10:11], 0, v[180:181]
	v_lshl_add_u64 v[98:99], v[166:167], 1, v[82:83]
	global_store_dwordx4 v[98:99], v[90:93], off
	v_cvt_pk_bf16_f32 v84, v86, v87
	s_waitcnt lgkmcnt(0)
	v_add_f32_e32 v82, v85, v100
	v_mov_b32_e32 v83, v82
	s_nop 1
	v_permlane32_swap_b32 v82, v83
	s_nop 1
	v_cvt_pk_bf16_f32 v85, v88, v89
	v_cvt_pk_bf16_f32 v86, v96, v97
	v_cvt_pk_bf16_f32 v87, v94, v95
	global_store_dwordx4 v[98:99], v[84:87], off offset:256
	s_and_saveexec_b64 s[8:9], vcc
	s_cbranch_execz .LBB0_1369
	s_waitcnt lgkmcnt(0)
	v_add_f32_e32 v82, v82, v83
	ds_write_b32 v128, v82 offset:512
.LBB0_1369:
	s_or_b64 exec, exec, s[8:9]
	v_lshlrev_b32_e32 v82, 16, v118
	s_waitcnt lgkmcnt(0)
	v_and_b32_e32 v83, 0xffff0000, v118
	v_lshlrev_b32_e32 v84, 16, v119
	v_and_b32_e32 v85, 0xffff0000, v119
	v_lshlrev_b32_e32 v86, 16, v120
	v_and_b32_e32 v87, 0xffff0000, v120
	v_lshlrev_b32_e32 v88, 16, v121
	v_and_b32_e32 v89, 0xffff0000, v121
	v_pk_add_f32 v[80:81], v[80:81], v[84:85]
	v_pk_add_f32 v[78:79], v[78:79], v[82:83]
	v_pk_add_f32 v[82:83], v[76:77], v[88:89]
	v_pk_add_f32 v[76:77], v[74:75], v[86:87]
	v_mul_f32_e32 v74, v79, v79
	v_mul_f32_e32 v75, v81, v81
	v_fmac_f32_e32 v74, v78, v78
	v_fmac_f32_e32 v75, v80, v80
	v_add_f32_e32 v74, v74, v75
	v_mul_f32_e32 v75, v77, v77
	v_mul_f32_e32 v84, v83, v83
	v_fmac_f32_e32 v75, v76, v76
	v_fmac_f32_e32 v84, v82, v82
	v_add_f32_e32 v75, v75, v84
	v_add_f32_e32 v86, v74, v75
	v_cvt_pk_bf16_f32 v74, v78, v79
	v_cvt_pk_bf16_f32 v75, v80, v81
	v_lshlrev_b32_e32 v78, 16, v114
	v_and_b32_e32 v79, 0xffff0000, v114
	v_lshlrev_b32_e32 v80, 16, v115
	v_and_b32_e32 v81, 0xffff0000, v115
	v_cvt_pk_bf16_f32 v76, v76, v77
	v_cvt_pk_bf16_f32 v77, v82, v83
	v_lshlrev_b32_e32 v82, 16, v116
	v_and_b32_e32 v83, 0xffff0000, v116
	v_pk_add_f32 v[72:73], v[72:73], v[80:81]
	v_pk_add_f32 v[70:71], v[70:71], v[78:79]
	v_lshlrev_b32_e32 v84, 16, v117
	v_and_b32_e32 v85, 0xffff0000, v117
	v_pk_add_f32 v[80:81], v[66:67], v[82:83]
	v_mul_f32_e32 v66, v71, v71
	v_mul_f32_e32 v67, v73, v73
	v_pk_add_f32 v[78:79], v[68:69], v[84:85]
	v_fmac_f32_e32 v66, v70, v70
	v_fmac_f32_e32 v67, v72, v72
	v_add_f32_e32 v66, v66, v67
	v_mul_f32_e32 v67, v81, v81
	v_mul_f32_e32 v68, v79, v79
	v_fmac_f32_e32 v67, v80, v80
	v_fmac_f32_e32 v68, v78, v78
	v_add_f32_e32 v67, v67, v68
	v_add_f32_e32 v66, v66, v67
	v_add_f32_e32 v69, v86, v66
	ds_bpermute_b32 v84, v126, v69
	v_lshl_add_u64 v[66:67], s[10:11], 0, v[172:173]
	v_lshl_add_u64 v[82:83], v[166:167], 1, v[66:67]
	global_store_dwordx4 v[82:83], v[74:77], off
	v_cvt_pk_bf16_f32 v68, v70, v71
	s_waitcnt lgkmcnt(0)
	v_add_f32_e32 v66, v69, v84
	v_mov_b32_e32 v67, v66
	s_nop 1
	v_permlane32_swap_b32 v66, v67
	s_nop 1
	v_cvt_pk_bf16_f32 v69, v72, v73
	v_cvt_pk_bf16_f32 v70, v80, v81
	v_cvt_pk_bf16_f32 v71, v78, v79
	global_store_dwordx4 v[82:83], v[68:71], off offset:256
	s_and_saveexec_b64 s[8:9], vcc
	s_cbranch_execz .LBB0_1371
	s_waitcnt lgkmcnt(0)
	v_add_f32_e32 v66, v66, v67
	ds_write_b32 v128, v66 offset:768
; __device__ __forceinline__ unsigned cvt_pk_bf16(float lo, float hi) { unsigned r; asm volatile("v_cvt_pk_bf16_f32 %0, %1, %2" : "=v"(r) : "v"(lo), "v"(hi)); return r; }
;     __device__ __forceinline__ void operator()(const f32x4 (&acc)[2][2][4][2], const Unit& u, int wr, int wc, int fr, int fq) const {
;     ...
;             if (!base32) {
; #pragma unroll
;                 for (int m = 0; m < 4; ++m)
; #pragma unroll
;                     for (int bj = 0; bj < 2; ++bj) hv4[m][bj] = *(const u32x4*)(hb + (size_t)(row0 + ai * HALF + m * 16) * 1024 + col0 + bj * HALF);
;             }
; #pragma unroll
;             for (int m = 0; m < 4; ++m) { const int row = row0 + ai * HALF + m * 16; const size_t off = (size_t)row * 1024 + col0; float s = 0.f;
; #pragma unroll
;                 for (int bj = 0; bj < 2; ++bj) { f32x4 b0, b1;
;                     if (base32) { b0 = *(const f32x4*)(base32 + off + bj * HALF); b1 = *(const f32x4*)(base32 + off + bj * HALF + 4); }
;                     else { const u32x4 hv = hv4[m][bj];
;                         b0 = (f32x4){__builtin_bit_cast(float, hv.x << 16), __builtin_bit_cast(float, hv.x & 0xffff0000u), __builtin_bit_cast(float, hv.y << 16), __builtin_bit_cast(float, hv.y & 0xffff0000u)};
;                         b1 = (f32x4){__builtin_bit_cast(float, hv.z << 16), __builtin_bit_cast(float, hv.z & 0xffff0000u), __builtin_bit_cast(float, hv.w << 16), __builtin_bit_cast(float, hv.w & 0xffff0000u)}; }
;                     const f32x4 o0 = b0 + acc[ai][bj][m][0], o1 = b1 + acc[ai][bj][m][1];
;                     s += ((o0[0] * o0[0] + o0[1] * o0[1]) + (o0[2] * o0[2] + o0[3] * o0[3])) + ((o1[0] * o1[0] + o1[1] * o1[1]) + (o1[2] * o1[2] + o1[3] * o1[3]));
;                     u32x4 w; w.x = cvt_pk_bf16(o0[0], o0[1]); w.y = cvt_pk_bf16(o0[2], o0[3]); w.z = cvt_pk_bf16(o1[0], o1[1]); w.w = cvt_pk_bf16(o1[2], o1[3]); *(u32x4*)(hb + off + bj * HALF) = w; }
;                 s += __shfl_xor(s, 16); s += __shfl_xor(s, 32);
;                 if (fq == 0) P[(wr * 64 + ai * HALF + m * 16 + fr) * 4 + wc] = s;
.LBB0_1371:
	s_or_b64 exec, exec, s[8:9]
	s_waitcnt lgkmcnt(0)
	v_lshlrev_b64 v[66:67], 11, v[170:171]
	s_mov_b64 s[8:9], 0x40000
	v_lshl_add_u64 v[104:105], v[66:67], 0, s[8:9]
	v_lshl_add_u64 v[68:69], v[168:169], 0, v[104:105]
	global_load_dwordx4 v[96:99], v[68:69], off
	global_load_dwordx4 v[100:103], v[68:69], off offset:256
	s_mov_b64 s[8:9], 0x48000
	v_lshl_add_u64 v[94:95], v[66:67], 0, s[8:9]
	s_mov_b64 s[8:9], 0x50000
	v_lshl_add_u64 v[92:93], v[66:67], 0, s[8:9]
	s_mov_b64 s[8:9], 0x58000
	v_lshl_add_u64 v[68:69], v[168:169], 0, v[94:95]
	v_lshl_add_u64 v[90:91], v[66:67], 0, s[8:9]
	global_load_dwordx4 v[86:89], v[68:69], off
	global_load_dwordx4 v[82:85], v[68:69], off offset:256
	v_lshl_add_u64 v[68:69], v[168:169], 0, v[92:93]
	v_lshl_add_u64 v[66:67], v[168:169], 0, v[90:91]
	global_load_dwordx4 v[78:81], v[68:69], off
	global_load_dwordx4 v[74:77], v[68:69], off offset:256
	global_load_dwordx4 v[70:73], v[66:67], off
	s_nop 0
	global_load_dwordx4 v[66:69], v[66:67], off offset:256
	s_waitcnt vmcnt(7)
	v_lshlrev_b32_e32 v106, 16, v96
	v_and_b32_e32 v107, 0xffff0000, v96
	v_lshlrev_b32_e32 v96, 16, v97
	v_and_b32_e32 v97, 0xffff0000, v97
	v_lshlrev_b32_e32 v108, 16, v98
	v_and_b32_e32 v109, 0xffff0000, v98
	v_lshlrev_b32_e32 v98, 16, v99
	v_and_b32_e32 v99, 0xffff0000, v99
	v_pk_add_f32 v[64:65], v[64:65], v[96:97]
	v_pk_add_f32 v[62:63], v[62:63], v[106:107]
	v_pk_add_f32 v[96:97], v[60:61], v[98:99]
	v_mul_f32_e32 v60, v63, v63
	v_mul_f32_e32 v61, v65, v65
	v_pk_add_f32 v[58:59], v[58:59], v[108:109]
	v_fmac_f32_e32 v60, v62, v62
	v_fmac_f32_e32 v61, v64, v64
	v_add_f32_e32 v60, v60, v61
	v_mul_f32_e32 v61, v59, v59
	v_mul_f32_e32 v98, v97, v97
	v_fmac_f32_e32 v61, v58, v58
	v_fmac_f32_e32 v98, v96, v96
	v_add_f32_e32 v61, v61, v98
	v_add_f32_e32 v98, v60, v61
	v_cvt_pk_bf16_f32 v60, v62, v63
	v_cvt_pk_bf16_f32 v61, v64, v65
	v_cvt_pk_bf16_f32 v62, v58, v59
	v_lshl_add_u64 v[58:59], s[10:11], 0, v[104:105]
	v_cvt_pk_bf16_f32 v63, v96, v97
	v_lshl_add_u64 v[58:59], v[166:167], 1, v[58:59]
	global_store_dwordx4 v[58:59], v[60:63], off
	s_waitcnt vmcnt(7)
	v_lshlrev_b32_e32 v64, 16, v102
	v_and_b32_e32 v65, 0xffff0000, v102
	v_lshlrev_b32_e32 v60, 16, v100
	v_and_b32_e32 v61, 0xffff0000, v100
	v_lshlrev_b32_e32 v62, 16, v101
	v_and_b32_e32 v63, 0xffff0000, v101
	v_lshlrev_b32_e32 v96, 16, v103
	v_and_b32_e32 v97, 0xffff0000, v103
	v_pk_add_f32 v[56:57], v[56:57], v[62:63]
	v_pk_add_f32 v[54:55], v[54:55], v[60:61]
	v_pk_add_f32 v[60:61], v[52:53], v[96:97]
	v_pk_add_f32 v[52:53], v[50:51], v[64:65]
	v_mul_f32_e32 v50, v55, v55
	v_mul_f32_e32 v51, v57, v57
	v_fmac_f32_e32 v50, v54, v54
	v_fmac_f32_e32 v51, v56, v56
	v_add_f32_e32 v50, v50, v51
	v_mul_f32_e32 v51, v53, v53
	v_mul_f32_e32 v62, v61, v61
	v_fmac_f32_e32 v51, v52, v52
	v_fmac_f32_e32 v62, v60, v60
	v_add_f32_e32 v51, v51, v62
	v_add_f32_e32 v50, v50, v51
	v_add_f32_e32 v62, v98, v50
	v_cvt_pk_bf16_f32 v50, v54, v55
	v_cvt_pk_bf16_f32 v51, v56, v57
	v_cvt_pk_bf16_f32 v52, v52, v53
	v_cvt_pk_bf16_f32 v53, v60, v61
	global_store_dwordx4 v[58:59], v[50:53], off offset:256
	ds_bpermute_b32 v50, v126, v62
	s_waitcnt lgkmcnt(0)
	v_add_f32_e32 v50, v62, v50
	v_mov_b32_e32 v51, v50
	s_nop 1
	v_permlane32_swap_b32 v50, v51
	s_nop 1
	s_and_saveexec_b64 s[8:9], vcc
	s_cbranch_execz .LBB0_1373
	s_waitcnt lgkmcnt(0)
	v_add_f32_e32 v50, v50, v51
	ds_write_b32 v128, v50 offset:2048
.LBB0_1373:
	s_or_b64 exec, exec, s[8:9]
	s_waitcnt vmcnt(7)
	v_lshlrev_b32_e32 v50, 16, v86
	s_waitcnt lgkmcnt(0)
	v_and_b32_e32 v51, 0xffff0000, v86
	v_lshlrev_b32_e32 v52, 16, v87
	v_and_b32_e32 v53, 0xffff0000, v87
	v_lshlrev_b32_e32 v54, 16, v88
	v_and_b32_e32 v55, 0xffff0000, v88
	v_lshlrev_b32_e32 v56, 16, v89
	v_and_b32_e32 v57, 0xffff0000, v89
	v_pk_add_f32 v[48:49], v[48:49], v[52:53]
	v_pk_add_f32 v[46:47], v[46:47], v[50:51]
	v_pk_add_f32 v[50:51], v[44:45], v[56:57]
	v_pk_add_f32 v[44:45], v[42:43], v[54:55]
	v_mul_f32_e32 v42, v47, v47
	v_mul_f32_e32 v43, v49, v49
	v_fmac_f32_e32 v42, v46, v46
	v_fmac_f32_e32 v43, v48, v48
	v_add_f32_e32 v42, v42, v43
	v_mul_f32_e32 v43, v45, v45
	v_mul_f32_e32 v52, v51, v51
	v_fmac_f32_e32 v43, v44, v44
	v_fmac_f32_e32 v52, v50, v50
	v_add_f32_e32 v43, v43, v52
	v_add_f32_e32 v54, v42, v43
	v_cvt_pk_bf16_f32 v42, v46, v47
	v_cvt_pk_bf16_f32 v43, v48, v49
	s_waitcnt vmcnt(6)
	v_lshlrev_b32_e32 v46, 16, v82
	v_and_b32_e32 v47, 0xffff0000, v82
	v_lshlrev_b32_e32 v48, 16, v83
	v_and_b32_e32 v49, 0xffff0000, v83
	v_cvt_pk_bf16_f32 v44, v44, v45
	v_cvt_pk_bf16_f32 v45, v50, v51
	v_lshlrev_b32_e32 v50, 16, v84
	v_and_b32_e32 v51, 0xffff0000, v84
	v_pk_add_f32 v[40:41], v[40:41], v[48:49]
	v_pk_add_f32 v[38:39], v[38:39], v[46:47]
	v_lshlrev_b32_e32 v52, 16, v85
	v_and_b32_e32 v53, 0xffff0000, v85
	v_pk_add_f32 v[48:49], v[34:35], v[50:51]
	v_mul_f32_e32 v34, v39, v39
	v_mul_f32_e32 v35, v41, v41
	v_pk_add_f32 v[46:47], v[36:37], v[52:53]
	v_fmac_f32_e32 v34, v38, v38
	v_fmac_f32_e32 v35, v40, v40
	v_add_f32_e32 v34, v34, v35
	v_mul_f32_e32 v35, v49, v49
	v_mul_f32_e32 v36, v47, v47
	v_fmac_f32_e32 v35, v48, v48
	v_fmac_f32_e32 v36, v46, v46
	v_add_f32_e32 v35, v35, v36
	v_add_f32_e32 v34, v34, v35
	v_add_f32_e32 v37, v54, v34
	ds_bpermute_b32 v52, v126, v37
	v_lshl_add_u64 v[34:35], s[10:11], 0, v[94:95]
	v_lshl_add_u64 v[50:51], v[166:167], 1, v[34:35]
	global_store_dwordx4 v[50:51], v[42:45], off
	v_cvt_pk_bf16_f32 v36, v38, v39
	s_waitcnt lgkmcnt(0)
	v_add_f32_e32 v34, v37, v52
	v_mov_b32_e32 v35, v34
	s_nop 1
	v_permlane32_swap_b32 v34, v35
	s_nop 1
	v_cvt_pk_bf16_f32 v37, v40, v41
	v_cvt_pk_bf16_f32 v38, v48, v49
	v_cvt_pk_bf16_f32 v39, v46, v47
	global_store_dwordx4 v[50:51], v[36:39], off offset:256
	s_and_saveexec_b64 s[8:9], vcc
	s_cbranch_execz .LBB0_1375
	s_waitcnt lgkmcnt(0)
	v_add_f32_e32 v34, v34, v35
	ds_write_b32 v128, v34 offset:2304
; __device__ __forceinline__ unsigned cvt_pk_bf16(float lo, float hi) { unsigned r; asm volatile("v_cvt_pk_bf16_f32 %0, %1, %2" : "=v"(r) : "v"(lo), "v"(hi)); return r; }
;     __device__ __forceinline__ void operator()(const f32x4 (&acc)[2][2][4][2], const Unit& u, int wr, int wc, int fr, int fq) const {
;     ...
;             for (int m = 0; m < 4; ++m) { const int row = row0 + ai * HALF + m * 16; const size_t off = (size_t)row * 1024 + col0; float s = 0.f;
; #pragma unroll
;                 for (int bj = 0; bj < 2; ++bj) { f32x4 b0, b1;
;                     if (base32) { b0 = *(const f32x4*)(base32 + off + bj * HALF); b1 = *(const f32x4*)(base32 + off + bj * HALF + 4); }
;                     else { const u32x4 hv = hv4[m][bj];
;                         b0 = (f32x4){__builtin_bit_cast(float, hv.x << 16), __builtin_bit_cast(float, hv.x & 0xffff0000u), __builtin_bit_cast(float, hv.y << 16), __builtin_bit_cast(float, hv.y & 0xffff0000u)};
;                         b1 = (f32x4){__builtin_bit_cast(float, hv.z << 16), __builtin_bit_cast(float, hv.z & 0xffff0000u), __builtin_bit_cast(float, hv.w << 16), __builtin_bit_cast(float, hv.w & 0xffff0000u)}; }
;                     const f32x4 o0 = b0 + acc[ai][bj][m][0], o1 = b1 + acc[ai][bj][m][1];
;                     s += ((o0[0] * o0[0] + o0[1] * o0[1]) + (o0[2] * o0[2] + o0[3] * o0[3])) + ((o1[0] * o1[0] + o1[1] * o1[1]) + (o1[2] * o1[2] + o1[3] * o1[3]));
;                     u32x4 w; w.x = cvt_pk_bf16(o0[0], o0[1]); w.y = cvt_pk_bf16(o0[2], o0[3]); w.z = cvt_pk_bf16(o1[0], o1[1]); w.w = cvt_pk_bf16(o1[2], o1[3]); *(u32x4*)(hb + off + bj * HALF) = w; }
;                 s += __shfl_xor(s, 16); s += __shfl_xor(s, 32);
;                 if (fq == 0) P[(wr * 64 + ai * HALF + m * 16 + fr) * 4 + wc] = s;
.LBB0_1375:
	s_or_b64 exec, exec, s[8:9]
	s_waitcnt vmcnt(7)
	v_lshlrev_b32_e32 v34, 16, v78
	s_waitcnt lgkmcnt(0)
	v_and_b32_e32 v35, 0xffff0000, v78
	v_lshlrev_b32_e32 v36, 16, v79
	v_and_b32_e32 v37, 0xffff0000, v79
	v_lshlrev_b32_e32 v38, 16, v80
	v_and_b32_e32 v39, 0xffff0000, v80
	v_lshlrev_b32_e32 v40, 16, v81
	v_and_b32_e32 v41, 0xffff0000, v81
	v_pk_add_f32 v[32:33], v[32:33], v[36:37]
	v_pk_add_f32 v[30:31], v[30:31], v[34:35]
	v_pk_add_f32 v[34:35], v[28:29], v[40:41]
	v_pk_add_f32 v[28:29], v[26:27], v[38:39]
	v_mul_f32_e32 v26, v31, v31
	v_mul_f32_e32 v27, v33, v33
	v_fmac_f32_e32 v26, v30, v30
	v_fmac_f32_e32 v27, v32, v32
	v_add_f32_e32 v26, v26, v27
	v_mul_f32_e32 v27, v29, v29
	v_mul_f32_e32 v36, v35, v35
	v_fmac_f32_e32 v27, v28, v28
	v_fmac_f32_e32 v36, v34, v34
	v_add_f32_e32 v27, v27, v36
	v_add_f32_e32 v38, v26, v27
	v_cvt_pk_bf16_f32 v26, v30, v31
	v_cvt_pk_bf16_f32 v27, v32, v33
	s_waitcnt vmcnt(6)
	v_lshlrev_b32_e32 v30, 16, v74
	v_and_b32_e32 v31, 0xffff0000, v74
	v_lshlrev_b32_e32 v32, 16, v75
	v_and_b32_e32 v33, 0xffff0000, v75
	v_cvt_pk_bf16_f32 v28, v28, v29
	v_cvt_pk_bf16_f32 v29, v34, v35
	v_lshlrev_b32_e32 v34, 16, v76
	v_and_b32_e32 v35, 0xffff0000, v76
	v_pk_add_f32 v[24:25], v[24:25], v[32:33]
	v_pk_add_f32 v[22:23], v[22:23], v[30:31]
	v_lshlrev_b32_e32 v36, 16, v77
	v_and_b32_e32 v37, 0xffff0000, v77
	v_pk_add_f32 v[32:33], v[18:19], v[34:35]
	v_mul_f32_e32 v18, v23, v23
	v_mul_f32_e32 v19, v25, v25
	v_pk_add_f32 v[30:31], v[20:21], v[36:37]
	v_fmac_f32_e32 v18, v22, v22
	v_fmac_f32_e32 v19, v24, v24
	v_add_f32_e32 v18, v18, v19
	v_mul_f32_e32 v19, v33, v33
	v_mul_f32_e32 v20, v31, v31
	v_fmac_f32_e32 v19, v32, v32
	v_fmac_f32_e32 v20, v30, v30
	v_add_f32_e32 v19, v19, v20
	v_add_f32_e32 v18, v18, v19
	v_add_f32_e32 v21, v38, v18
	ds_bpermute_b32 v36, v126, v21
	v_lshl_add_u64 v[18:19], s[10:11], 0, v[92:93]
	v_lshl_add_u64 v[34:35], v[166:167], 1, v[18:19]
	global_store_dwordx4 v[34:35], v[26:29], off
	v_cvt_pk_bf16_f32 v20, v22, v23
	s_waitcnt lgkmcnt(0)
	v_add_f32_e32 v18, v21, v36
	v_mov_b32_e32 v19, v18
	s_nop 1
	v_permlane32_swap_b32 v18, v19
	s_nop 1
	v_cvt_pk_bf16_f32 v21, v24, v25
	v_cvt_pk_bf16_f32 v22, v32, v33
	v_cvt_pk_bf16_f32 v23, v30, v31
	global_store_dwordx4 v[34:35], v[20:23], off offset:256
	s_and_saveexec_b64 s[8:9], vcc
	s_cbranch_execz .LBB0_1377
	s_waitcnt lgkmcnt(0)
	v_add_f32_e32 v18, v18, v19
	ds_write_b32 v128, v18 offset:2560
.LBB0_1377:
	s_or_b64 exec, exec, s[8:9]
	s_waitcnt vmcnt(7)
	v_lshlrev_b32_e32 v18, 16, v70
	s_waitcnt lgkmcnt(0)
	v_and_b32_e32 v19, 0xffff0000, v70
	v_lshlrev_b32_e32 v20, 16, v71
	v_and_b32_e32 v21, 0xffff0000, v71
	v_lshlrev_b32_e32 v22, 16, v72
	v_and_b32_e32 v23, 0xffff0000, v72
	v_lshlrev_b32_e32 v24, 16, v73
	v_and_b32_e32 v25, 0xffff0000, v73
	v_pk_add_f32 v[16:17], v[16:17], v[20:21]
	v_pk_add_f32 v[14:15], v[14:15], v[18:19]
	v_pk_add_f32 v[18:19], v[12:13], v[24:25]
	v_pk_add_f32 v[12:13], v[10:11], v[22:23]
	v_mul_f32_e32 v10, v15, v15
	v_mul_f32_e32 v11, v17, v17
	v_fmac_f32_e32 v10, v14, v14
	v_fmac_f32_e32 v11, v16, v16
	v_add_f32_e32 v10, v10, v11
	v_mul_f32_e32 v11, v13, v13
	v_mul_f32_e32 v20, v19, v19
	v_fmac_f32_e32 v11, v12, v12
	v_fmac_f32_e32 v20, v18, v18
	v_add_f32_e32 v11, v11, v20
	v_add_f32_e32 v22, v10, v11
	v_cvt_pk_bf16_f32 v10, v14, v15
	v_cvt_pk_bf16_f32 v11, v16, v17
	s_waitcnt vmcnt(6)
	v_lshlrev_b32_e32 v14, 16, v66
	v_and_b32_e32 v15, 0xffff0000, v66
	v_lshlrev_b32_e32 v16, 16, v67
	v_and_b32_e32 v17, 0xffff0000, v67
	v_cvt_pk_bf16_f32 v12, v12, v13
	v_cvt_pk_bf16_f32 v13, v18, v19
	v_lshlrev_b32_e32 v18, 16, v68
	v_and_b32_e32 v19, 0xffff0000, v68
	v_pk_add_f32 v[8:9], v[8:9], v[16:17]
	v_pk_add_f32 v[6:7], v[6:7], v[14:15]
	v_lshlrev_b32_e32 v20, 16, v69
	v_and_b32_e32 v21, 0xffff0000, v69
	v_pk_add_f32 v[16:17], v[2:3], v[18:19]
	v_mul_f32_e32 v2, v7, v7
	v_mul_f32_e32 v3, v9, v9
	v_pk_add_f32 v[14:15], v[4:5], v[20:21]
	v_fmac_f32_e32 v2, v6, v6
	v_fmac_f32_e32 v3, v8, v8
	v_add_f32_e32 v2, v2, v3
	v_mul_f32_e32 v3, v17, v17
	v_mul_f32_e32 v4, v15, v15
	v_fmac_f32_e32 v3, v16, v16
	v_fmac_f32_e32 v4, v14, v14
	v_add_f32_e32 v3, v3, v4
	v_add_f32_e32 v2, v2, v3
	v_add_f32_e32 v5, v22, v2
	ds_bpermute_b32 v20, v126, v5
	v_lshl_add_u64 v[2:3], s[10:11], 0, v[90:91]
	v_lshl_add_u64 v[18:19], v[166:167], 1, v[2:3]
	global_store_dwordx4 v[18:19], v[10:13], off
	v_cvt_pk_bf16_f32 v4, v6, v7
	s_waitcnt lgkmcnt(0)
	v_add_f32_e32 v2, v5, v20
	v_mov_b32_e32 v3, v2
	s_nop 1
	v_permlane32_swap_b32 v2, v3
	s_nop 1
	v_cvt_pk_bf16_f32 v5, v8, v9
	v_cvt_pk_bf16_f32 v6, v16, v17
	v_cvt_pk_bf16_f32 v7, v14, v15
	global_store_dwordx4 v[18:19], v[4:7], off offset:256
	s_and_saveexec_b64 s[8:9], vcc
	s_cbranch_execz .LBB0_1379
	s_waitcnt lgkmcnt(0)
	v_add_f32_e32 v2, v2, v3
	ds_write_b32 v128, v2 offset:2816
